# v9 + K-loops of FFN-up L0a, even-out and FFN-up L0b shifted by 4 bytes so that most of their 8-byte instructions are 8-byte aligned (one s_nop before the head, one after the exit)
# baseline (speedup 1.0000x reference)
; #define PG8_STAGE(bufoff, gbase, voff) do { _Pragma("unroll") for (int _i = 0; _i < 2; ++_i) \
;         __builtin_amdgcn_global_load_lds((const unsigned*)((const char*)(gbase) + (voff)[_i]), (PG8_LAS unsigned*)(lds + (bufoff) + ldsw + _i * 8192), 16, 0, 0); } while (0)
; #define PG8_SCHED __builtin_amdgcn_sched_barrier(0)
;     __device__ __forceinline__ int nt(const pg8::Unit& u) const { return u.kind == 0 ? ntiles : q_nt(u.kind - 1); }
;     __device__ __forceinline__ const char* a_base(const pg8::Unit& u) const { return A + (size_t)u.pm * tstep + (u.kind > 1 ? (size_t)q_off(u.kind - 1) * 128 : 0); }
;     __device__ __forceinline__ const char* b_base(const pg8::Unit& u) const { return Bt + (size_t)u.pn * tstep + (u.kind > 1 ? (size_t)q_off(u.kind - 1) * 128 : 0); }
; template <class Epi, class Sched, bool ALIGN_EPI = true, bool SP2 = true>
; __device__ __forceinline__ void gemm_phase(PG8_LAS unsigned char* lds, const int K  , const Sched& S, const Epi& E) {
;     ...
;         const bool has_next = S.next(ui + 1, nxt);
;         const int nt = S.nt(cur);
;         const char* nA = has_next ? S.a_base(nxt) : cA; const char* nB = has_next ? S.b_base(nxt) : cB;
;         for (int t = 0; t < nt; t += 2) {
;             const bool last = (t == nt - 2);
;             const char* a1 = cA + (size_t)(t + 1) * kstep;
;             const char* a2 = last ? nA : cA + (size_t)(t + 2) * kstep; const char* b2 = last ? nB : cB + (size_t)(t + 2) * kstep;
;             const char* a3 = a2 + kstep; const char* b3 = b2 + kstep;
;             if constexpr (SP2) {
;             PG8_LDB(B0, 0, 0); PG8_LDB(B1, 0, 1); PG8_SCHED; PG8_LDA(At, 0, 0); PG8_STAGE(PG8_SA(1, 1), a1 + hstep, voffA);
;     ...
; #pragma unroll
;         for (int a = 0; a < 2; ++a)
; #pragma unroll
;             for (int b = 0; b < 2; ++b)
; #pragma unroll
;                 for (int m = 0; m < 4; ++m)
; #pragma unroll
;                     for (int n = 0; n < 2; ++n) acc[a][b][m][n] = (f32x4){0.f, 0.f, 0.f, 0.f};
.LBB0_218:
	s_ashr_i32 s13, s12, 31
	s_lshl_b64 s[14:15], s[12:13], 20
	v_readlane_b32 s11, v253, 48
	s_add_u32 s14, s11, s14
	v_readlane_b32 s11, v253, 49
	s_addc_u32 s15, s11, s15
	s_and_b64 s[16:17], s[0:1], exec
	s_cselect_b32 s13, s15, s21
	s_cselect_b32 s44, s14, s20
	s_ashr_i32 s11, s10, 31
	s_lshl_b64 s[16:17], s[10:11], 20
	s_add_u32 s16, s27, s16
	s_addc_u32 s17, s28, s17
	s_and_b64 s[24:25], s[0:1], exec
	s_cselect_b32 s11, s17, s23
	s_cselect_b32 s45, s16, s22
	s_add_u32 s20, s20, 0x80080
	s_addc_u32 s21, s21, 0
	s_add_u32 s46, s22, 0x100
	v_mov_b32_e32 v2, 0
	s_addc_u32 s47, s23, 0
	s_mov_b32 s48, -2
	v_mov_b32_e32 v3, v2
	v_mov_b32_e32 v4, v2
	v_mov_b32_e32 v5, v2
	v_mov_b32_e32 v10, v2
	v_mov_b32_e32 v11, v2
	v_mov_b32_e32 v12, v2
	v_mov_b32_e32 v13, v2
	v_mov_b32_e32 v18, v2
	v_mov_b32_e32 v19, v2
	v_mov_b32_e32 v20, v2
	v_mov_b32_e32 v21, v2
	v_mov_b32_e32 v26, v2
	v_mov_b32_e32 v27, v2
	v_mov_b32_e32 v28, v2
	v_mov_b32_e32 v29, v2
	v_mov_b32_e32 v34, v2
	v_mov_b32_e32 v35, v2
	v_mov_b32_e32 v36, v2
	v_mov_b32_e32 v37, v2
	v_mov_b32_e32 v42, v2
	v_mov_b32_e32 v43, v2
	v_mov_b32_e32 v44, v2
	v_mov_b32_e32 v45, v2
	v_mov_b32_e32 v50, v2
	v_mov_b32_e32 v51, v2
	v_mov_b32_e32 v52, v2
	v_mov_b32_e32 v53, v2
	v_mov_b32_e32 v58, v2
	v_mov_b32_e32 v59, v2
	v_mov_b32_e32 v60, v2
	v_mov_b32_e32 v61, v2
	v_mov_b32_e32 v6, v2
	v_mov_b32_e32 v7, v2
	v_mov_b32_e32 v8, v2
	v_mov_b32_e32 v9, v2
	v_mov_b32_e32 v14, v2
	v_mov_b32_e32 v15, v2
	v_mov_b32_e32 v16, v2
	v_mov_b32_e32 v17, v2
	v_mov_b32_e32 v22, v2
	v_mov_b32_e32 v23, v2
	v_mov_b32_e32 v24, v2
	v_mov_b32_e32 v25, v2
	v_mov_b32_e32 v30, v2
	v_mov_b32_e32 v31, v2
	v_mov_b32_e32 v32, v2
	v_mov_b32_e32 v33, v2
	v_mov_b32_e32 v38, v2
	v_mov_b32_e32 v39, v2
	v_mov_b32_e32 v40, v2
	v_mov_b32_e32 v41, v2
	v_mov_b32_e32 v46, v2
	v_mov_b32_e32 v47, v2
	v_mov_b32_e32 v48, v2
	v_mov_b32_e32 v49, v2
	v_mov_b32_e32 v54, v2
	v_mov_b32_e32 v55, v2
	v_mov_b32_e32 v56, v2
	v_mov_b32_e32 v57, v2
	v_mov_b32_e32 v62, v2
	v_mov_b32_e32 v63, v2
	v_mov_b32_e32 v64, v2
	v_mov_b32_e32 v65, v2
	v_mov_b32_e32 v66, v2
	v_mov_b32_e32 v67, v2
	v_mov_b32_e32 v68, v2
	v_mov_b32_e32 v69, v2
	v_mov_b32_e32 v74, v2
	v_mov_b32_e32 v75, v2
	v_mov_b32_e32 v76, v2
	v_mov_b32_e32 v77, v2
	v_mov_b32_e32 v82, v2
	v_mov_b32_e32 v83, v2
	v_mov_b32_e32 v84, v2
	v_mov_b32_e32 v85, v2
	v_mov_b32_e32 v90, v2
	v_mov_b32_e32 v91, v2
	v_mov_b32_e32 v92, v2
	v_mov_b32_e32 v93, v2
	v_mov_b32_e32 v98, v2
	v_mov_b32_e32 v99, v2
	v_mov_b32_e32 v100, v2
	v_mov_b32_e32 v101, v2
	v_mov_b32_e32 v106, v2
	v_mov_b32_e32 v107, v2
	v_mov_b32_e32 v108, v2
	v_mov_b32_e32 v109, v2
	v_mov_b32_e32 v114, v2
	v_mov_b32_e32 v115, v2
	v_mov_b32_e32 v116, v2
	v_mov_b32_e32 v117, v2
	v_mov_b32_e32 v122, v2
	v_mov_b32_e32 v123, v2
	v_mov_b32_e32 v124, v2
	v_mov_b32_e32 v125, v2
	v_mov_b32_e32 v70, v2
	v_mov_b32_e32 v71, v2
	v_mov_b32_e32 v72, v2
	v_mov_b32_e32 v73, v2
	v_mov_b32_e32 v78, v2
	v_mov_b32_e32 v79, v2
	v_mov_b32_e32 v80, v2
	v_mov_b32_e32 v81, v2
	v_mov_b32_e32 v86, v2
	v_mov_b32_e32 v87, v2
	v_mov_b32_e32 v88, v2
	v_mov_b32_e32 v89, v2
	v_mov_b32_e32 v94, v2
	v_mov_b32_e32 v95, v2
	v_mov_b32_e32 v96, v2
	v_mov_b32_e32 v97, v2
	v_mov_b32_e32 v102, v2
	v_mov_b32_e32 v103, v2
	v_mov_b32_e32 v104, v2
	v_mov_b32_e32 v105, v2
	v_mov_b32_e32 v110, v2
	v_mov_b32_e32 v111, v2
	v_mov_b32_e32 v112, v2
	v_mov_b32_e32 v113, v2
	v_mov_b32_e32 v118, v2
	v_mov_b32_e32 v119, v2
	v_mov_b32_e32 v120, v2
	v_mov_b32_e32 v121, v2
	v_mov_b32_e32 v126, v2
	v_mov_b32_e32 v127, v2
	v_mov_b32_e32 v128, v2
	v_mov_b32_e32 v129, v2
	s_nop 0
.LBB0_219:
	ds_read_b128 v[148:151], v154
	ds_read_b128 v[160:163], v154 offset:1024
	ds_read_b128 v[164:167], v154 offset:2048
	ds_read_b128 v[168:171], v154 offset:3072
	ds_read_b128 v[172:175], v155
	ds_read_b128 v[176:179], v155 offset:1024
	ds_read_b128 v[180:183], v155 offset:2048
	ds_read_b128 v[184:187], v155 offset:3072
	s_add_u32 s22, s20, 0xfff80080
	s_addc_u32 s23, s21, -1
	s_cmp_eq_u32 s48, 28
	s_cselect_b32 s25, s13, s23
	s_cselect_b32 s24, s44, s22
	s_cselect_b32 s23, s11, s47
	s_cselect_b32 s22, s45, s46
	v_lshl_add_u64 v[220:221], s[20:21], 0, v[140:141]
	s_add_i32 m0, s19, 0xc000
	ds_read_b128 v[188:191], v156
	ds_read_b128 v[192:195], v156 offset:1024
	ds_read_b128 v[196:199], v156 offset:2048
	ds_read_b128 v[200:203], v156 offset:3072
	ds_read_b128 v[204:207], v156 offset:4096
	ds_read_b128 v[208:211], v156 offset:5120
	ds_read_b128 v[212:215], v156 offset:6144
	ds_read_b128 v[216:219], v156 offset:7168
	global_load_lds_dwordx4 v[220:221], off
	v_lshl_add_u64 v[220:221], s[20:21], 0, v[142:143]
	s_add_i32 m0, s19, 0xe000
	s_nop 0
	global_load_lds_dwordx4 v[220:221], off
	s_waitcnt vmcnt(8)
	s_waitcnt lgkmcnt(0)
	s_barrier
; #define PG8_STAGE(bufoff, gbase, voff) do { _Pragma("unroll") for (int _i = 0; _i < 2; ++_i) \
;         __builtin_amdgcn_global_load_lds((const unsigned*)((const char*)(gbase) + (voff)[_i]), (PG8_LAS unsigned*)(lds + (bufoff) + ldsw + _i * 8192), 16, 0, 0); } while (0)
; #define PG8_WAIT_V(n) asm volatile("s_waitcnt vmcnt(" #n ")" ::: "memory")
; #define PG8_WAIT_L(n) asm volatile("s_waitcnt lgkmcnt(" #n ")" ::: "memory")
; #define PG8_BAR __builtin_amdgcn_s_barrier()
; #define PG8_SCHED __builtin_amdgcn_sched_barrier(0)
; template <class Epi, class Sched, bool ALIGN_EPI = true, bool SP2 = true>
; __device__ __forceinline__ void gemm_phase(PG8_LAS unsigned char* lds, const int K  , const Sched& S, const Epi& E) {
;     ...
;             PG8_WAIT_V(8); PG8_WAIT_L(0); PG8_BAR; PG8_MMA(0, 0, At, B0); PG8_MMA(0, 1, At, B1); PG8_BAR; PG8_SCHED;
;             PG8_LDA(At, 0, 1); PG8_STAGE(PG8_SB(0, 0), b2, voffB); PG8_STAGE(PG8_SB(0, 1), b2 + hstep, voffB); PG8_STAGE(PG8_SA(0, 0), a2, voffA);
;             PG8_WAIT_V(8); PG8_WAIT_L(0); PG8_BAR; PG8_MMA(1, 0, At, B0); PG8_MMA(1, 1, At, B1); PG8_BAR; PG8_SCHED;
	s_setprio 1
	s_waitcnt lgkmcnt(0)
	v_mfma_f32_16x16x32_bf16 v[126:129], v[148:151], v[188:191], v[126:129]
	v_mfma_f32_16x16x32_bf16 v[118:121], v[164:167], v[188:191], v[118:121]
	v_mfma_f32_16x16x32_bf16 v[110:113], v[148:151], v[196:199], v[110:113]
	v_mfma_f32_16x16x32_bf16 v[102:105], v[164:167], v[196:199], v[102:105]
	v_mfma_f32_16x16x32_bf16 v[94:97], v[148:151], v[204:207], v[94:97]
	v_mfma_f32_16x16x32_bf16 v[86:89], v[164:167], v[204:207], v[86:89]
	v_mfma_f32_16x16x32_bf16 v[78:81], v[148:151], v[212:215], v[78:81]
	v_mfma_f32_16x16x32_bf16 v[70:73], v[164:167], v[212:215], v[70:73]
	v_mfma_f32_16x16x32_bf16 v[126:129], v[160:163], v[192:195], v[126:129]
	v_mfma_f32_16x16x32_bf16 v[118:121], v[168:171], v[192:195], v[118:121]
	v_mfma_f32_16x16x32_bf16 v[110:113], v[160:163], v[200:203], v[110:113]
	v_mfma_f32_16x16x32_bf16 v[102:105], v[168:171], v[200:203], v[102:105]
	v_mfma_f32_16x16x32_bf16 v[94:97], v[160:163], v[208:211], v[94:97]
	v_mfma_f32_16x16x32_bf16 v[86:89], v[168:171], v[208:211], v[86:89]
	v_mfma_f32_16x16x32_bf16 v[78:81], v[160:163], v[216:219], v[78:81]
	v_mfma_f32_16x16x32_bf16 v[70:73], v[168:171], v[216:219], v[70:73]
	s_setprio 0
	s_setprio 1
	v_mfma_f32_16x16x32_bf16 v[122:125], v[172:175], v[188:191], v[122:125]
	v_mfma_f32_16x16x32_bf16 v[114:117], v[180:183], v[188:191], v[114:117]
	v_mfma_f32_16x16x32_bf16 v[106:109], v[172:175], v[196:199], v[106:109]
	v_mfma_f32_16x16x32_bf16 v[98:101], v[180:183], v[196:199], v[98:101]
	v_mfma_f32_16x16x32_bf16 v[90:93], v[172:175], v[204:207], v[90:93]
	v_mfma_f32_16x16x32_bf16 v[82:85], v[180:183], v[204:207], v[82:85]
	v_mfma_f32_16x16x32_bf16 v[74:77], v[172:175], v[212:215], v[74:77]
	v_mfma_f32_16x16x32_bf16 v[66:69], v[180:183], v[212:215], v[66:69]
	v_mfma_f32_16x16x32_bf16 v[122:125], v[176:179], v[192:195], v[122:125]
	v_mfma_f32_16x16x32_bf16 v[114:117], v[184:187], v[192:195], v[114:117]
	v_mfma_f32_16x16x32_bf16 v[106:109], v[176:179], v[200:203], v[106:109]
	v_mfma_f32_16x16x32_bf16 v[98:101], v[184:187], v[200:203], v[98:101]
	v_mfma_f32_16x16x32_bf16 v[90:93], v[176:179], v[208:211], v[90:93]
	v_mfma_f32_16x16x32_bf16 v[82:85], v[184:187], v[208:211], v[82:85]
	v_mfma_f32_16x16x32_bf16 v[74:77], v[176:179], v[216:219], v[74:77]
	v_mfma_f32_16x16x32_bf16 v[66:69], v[184:187], v[216:219], v[66:69]
	s_setprio 0
	s_barrier
	s_add_i32 s49, s39, s29
	v_lshl_add_u64 v[220:221], s[22:23], 0, v[136:137]
	s_mov_b32 m0, s49
	ds_read_b128 v[188:191], v156 offset:16384
	ds_read_b128 v[192:195], v156 offset:17408
	ds_read_b128 v[196:199], v156 offset:18432
	ds_read_b128 v[200:203], v156 offset:19456
	ds_read_b128 v[204:207], v156 offset:20480
	ds_read_b128 v[208:211], v156 offset:21504
	ds_read_b128 v[212:215], v156 offset:22528
	ds_read_b128 v[216:219], v156 offset:23552
	global_load_lds_dwordx4 v[220:221], off
	s_add_i32 m0, s49, 0x2000
	s_add_u32 s50, s22, 0x80000
	v_lshl_add_u64 v[222:223], s[22:23], 0, v[132:133]
	s_addc_u32 s51, s23, 0
	s_add_i32 s49, s40, s29
	global_load_lds_dwordx4 v[222:223], off
	v_lshl_add_u64 v[224:225], s[50:51], 0, v[136:137]
	s_mov_b32 m0, s49
	v_lshl_add_u64 v[226:227], s[24:25], 0, v[134:135]
	global_load_lds_dwordx4 v[224:225], off
	v_lshl_add_u64 v[224:225], s[50:51], 0, v[132:133]
	s_add_i32 m0, s49, 0x2000
	s_nop 0
	global_load_lds_dwordx4 v[224:225], off
	v_lshl_add_u64 v[224:225], s[24:25], 0, v[138:139]
	s_mov_b32 m0, s19
	s_nop 0
	global_load_lds_dwordx4 v[224:225], off
	s_mov_b32 m0, s31
	s_nop 0
	global_load_lds_dwordx4 v[226:227], off
	s_waitcnt vmcnt(8)
	s_waitcnt lgkmcnt(0)
	s_barrier
	s_setprio 1
	s_waitcnt lgkmcnt(0)
	v_mfma_f32_16x16x32_bf16 v[62:65], v[148:151], v[188:191], v[62:65]
	v_mfma_f32_16x16x32_bf16 v[54:57], v[164:167], v[188:191], v[54:57]
	v_mfma_f32_16x16x32_bf16 v[46:49], v[148:151], v[196:199], v[46:49]
	v_mfma_f32_16x16x32_bf16 v[38:41], v[164:167], v[196:199], v[38:41]
	v_mfma_f32_16x16x32_bf16 v[30:33], v[148:151], v[204:207], v[30:33]
	v_mfma_f32_16x16x32_bf16 v[22:25], v[164:167], v[204:207], v[22:25]
	v_mfma_f32_16x16x32_bf16 v[14:17], v[148:151], v[212:215], v[14:17]
	v_mfma_f32_16x16x32_bf16 v[6:9], v[164:167], v[212:215], v[6:9]
	v_mfma_f32_16x16x32_bf16 v[62:65], v[160:163], v[192:195], v[62:65]
	v_mfma_f32_16x16x32_bf16 v[54:57], v[168:171], v[192:195], v[54:57]
	v_mfma_f32_16x16x32_bf16 v[46:49], v[160:163], v[200:203], v[46:49]
	v_mfma_f32_16x16x32_bf16 v[38:41], v[168:171], v[200:203], v[38:41]
	v_mfma_f32_16x16x32_bf16 v[30:33], v[160:163], v[208:211], v[30:33]
	v_mfma_f32_16x16x32_bf16 v[22:25], v[168:171], v[208:211], v[22:25]
	v_mfma_f32_16x16x32_bf16 v[14:17], v[160:163], v[216:219], v[14:17]
	v_mfma_f32_16x16x32_bf16 v[6:9], v[168:171], v[216:219], v[6:9]
	s_setprio 0
	s_setprio 1
	v_mfma_f32_16x16x32_bf16 v[58:61], v[172:175], v[188:191], v[58:61]
	v_mfma_f32_16x16x32_bf16 v[50:53], v[180:183], v[188:191], v[50:53]
	v_mfma_f32_16x16x32_bf16 v[42:45], v[172:175], v[196:199], v[42:45]
	v_mfma_f32_16x16x32_bf16 v[34:37], v[180:183], v[196:199], v[34:37]
	v_mfma_f32_16x16x32_bf16 v[26:29], v[172:175], v[204:207], v[26:29]
	v_mfma_f32_16x16x32_bf16 v[18:21], v[180:183], v[204:207], v[18:21]
	v_mfma_f32_16x16x32_bf16 v[10:13], v[172:175], v[212:215], v[10:13]
	v_mfma_f32_16x16x32_bf16 v[2:5], v[180:183], v[212:215], v[2:5]
	v_mfma_f32_16x16x32_bf16 v[58:61], v[176:179], v[192:195], v[58:61]
	v_mfma_f32_16x16x32_bf16 v[50:53], v[184:187], v[192:195], v[50:53]
	v_mfma_f32_16x16x32_bf16 v[42:45], v[176:179], v[200:203], v[42:45]
	v_mfma_f32_16x16x32_bf16 v[34:37], v[184:187], v[200:203], v[34:37]
	v_mfma_f32_16x16x32_bf16 v[26:29], v[176:179], v[208:211], v[26:29]
	v_mfma_f32_16x16x32_bf16 v[18:21], v[184:187], v[208:211], v[18:21]
	v_mfma_f32_16x16x32_bf16 v[10:13], v[176:179], v[216:219], v[10:13]
	v_mfma_f32_16x16x32_bf16 v[2:5], v[184:187], v[216:219], v[2:5]
	s_setprio 0
	s_barrier
; #define PG8_STAGE(bufoff, gbase, voff) do { _Pragma("unroll") for (int _i = 0; _i < 2; ++_i) \
;         __builtin_amdgcn_global_load_lds((const unsigned*)((const char*)(gbase) + (voff)[_i]), (PG8_LAS unsigned*)(lds + (bufoff) + ldsw + _i * 8192), 16, 0, 0); } while (0)
; #define PG8_WAIT_V(n) asm volatile("s_waitcnt vmcnt(" #n ")" ::: "memory")
; #define PG8_WAIT_L(n) asm volatile("s_waitcnt lgkmcnt(" #n ")" ::: "memory")
; #define PG8_BAR __builtin_amdgcn_s_barrier()
; #define PG8_SCHED __builtin_amdgcn_sched_barrier(0)
; template <class Epi, class Sched, bool ALIGN_EPI = true, bool SP2 = true>
; __device__ __forceinline__ void gemm_phase(PG8_LAS unsigned char* lds, const int K  , const Sched& S, const Epi& E) {
;     ...
;             PG8_LDB(B0, 1, 0); PG8_LDB(B1, 1, 1); PG8_SCHED; PG8_LDA(At, 1, 0); PG8_STAGE(PG8_SA(0, 1), a2 + hstep, voffA);
;             PG8_WAIT_V(8); PG8_WAIT_L(0); PG8_BAR; PG8_MMA(0, 0, At, B0); PG8_MMA(0, 1, At, B1); PG8_BAR; PG8_SCHED;
	s_add_i32 s49, 0, 0x18000
	v_add_u32_e32 v159, s49, v152
	s_add_i32 s50, 0, 0x1c000
	ds_read_b128 v[148:151], v159
	ds_read_b128 v[160:163], v159 offset:1024
	ds_read_b128 v[164:167], v159 offset:2048
	ds_read_b128 v[168:171], v159 offset:3072
	v_add_u32_e32 v159, s50, v152
	ds_read_b128 v[172:175], v159
	ds_read_b128 v[176:179], v159 offset:1024
	ds_read_b128 v[180:183], v159 offset:2048
	ds_read_b128 v[184:187], v159 offset:3072
	s_add_u32 s24, s24, 0x80000
	s_addc_u32 s25, s25, 0
	s_mov_b32 m0, s33
	v_lshl_add_u64 v[230:231], s[24:25], 0, v[138:139]
	ds_read_b128 v[188:191], v156 offset:32768
	ds_read_b128 v[192:195], v156 offset:33792
	ds_read_b128 v[196:199], v156 offset:34816
	ds_read_b128 v[200:203], v156 offset:35840
	ds_read_b128 v[204:207], v156 offset:36864
	ds_read_b128 v[208:211], v156 offset:37888
	ds_read_b128 v[212:215], v156 offset:38912
	ds_read_b128 v[216:219], v156 offset:39936
	global_load_lds_dwordx4 v[230:231], off
	v_lshl_add_u64 v[230:231], s[24:25], 0, v[134:135]
	s_mov_b32 m0, s34
	s_nop 0
	global_load_lds_dwordx4 v[230:231], off
	s_waitcnt vmcnt(8)
	s_waitcnt lgkmcnt(0)
	s_barrier
	s_setprio 1
	s_waitcnt lgkmcnt(0)
	v_mfma_f32_16x16x32_bf16 v[126:129], v[148:151], v[188:191], v[126:129]
	v_mfma_f32_16x16x32_bf16 v[118:121], v[164:167], v[188:191], v[118:121]
	v_mfma_f32_16x16x32_bf16 v[110:113], v[148:151], v[196:199], v[110:113]
	v_mfma_f32_16x16x32_bf16 v[102:105], v[164:167], v[196:199], v[102:105]
	v_mfma_f32_16x16x32_bf16 v[94:97], v[148:151], v[204:207], v[94:97]
	v_mfma_f32_16x16x32_bf16 v[86:89], v[164:167], v[204:207], v[86:89]
	v_mfma_f32_16x16x32_bf16 v[78:81], v[148:151], v[212:215], v[78:81]
	v_mfma_f32_16x16x32_bf16 v[70:73], v[164:167], v[212:215], v[70:73]
	v_mfma_f32_16x16x32_bf16 v[126:129], v[160:163], v[192:195], v[126:129]
	v_mfma_f32_16x16x32_bf16 v[118:121], v[168:171], v[192:195], v[118:121]
	v_mfma_f32_16x16x32_bf16 v[110:113], v[160:163], v[200:203], v[110:113]
	v_mfma_f32_16x16x32_bf16 v[102:105], v[168:171], v[200:203], v[102:105]
	v_mfma_f32_16x16x32_bf16 v[94:97], v[160:163], v[208:211], v[94:97]
	v_mfma_f32_16x16x32_bf16 v[86:89], v[168:171], v[208:211], v[86:89]
	v_mfma_f32_16x16x32_bf16 v[78:81], v[160:163], v[216:219], v[78:81]
	v_mfma_f32_16x16x32_bf16 v[70:73], v[168:171], v[216:219], v[70:73]
	s_setprio 0
	s_setprio 1
	v_mfma_f32_16x16x32_bf16 v[122:125], v[172:175], v[188:191], v[122:125]
	v_mfma_f32_16x16x32_bf16 v[114:117], v[180:183], v[188:191], v[114:117]
	v_mfma_f32_16x16x32_bf16 v[106:109], v[172:175], v[196:199], v[106:109]
	v_mfma_f32_16x16x32_bf16 v[98:101], v[180:183], v[196:199], v[98:101]
	v_mfma_f32_16x16x32_bf16 v[90:93], v[172:175], v[204:207], v[90:93]
	v_mfma_f32_16x16x32_bf16 v[82:85], v[180:183], v[204:207], v[82:85]
	v_mfma_f32_16x16x32_bf16 v[74:77], v[172:175], v[212:215], v[74:77]
	v_mfma_f32_16x16x32_bf16 v[66:69], v[180:183], v[212:215], v[66:69]
	v_mfma_f32_16x16x32_bf16 v[122:125], v[176:179], v[192:195], v[122:125]
	v_mfma_f32_16x16x32_bf16 v[114:117], v[184:187], v[192:195], v[114:117]
	v_mfma_f32_16x16x32_bf16 v[106:109], v[176:179], v[200:203], v[106:109]
	v_mfma_f32_16x16x32_bf16 v[98:101], v[184:187], v[200:203], v[98:101]
	v_mfma_f32_16x16x32_bf16 v[90:93], v[176:179], v[208:211], v[90:93]
	v_mfma_f32_16x16x32_bf16 v[82:85], v[184:187], v[208:211], v[82:85]
	v_mfma_f32_16x16x32_bf16 v[74:77], v[176:179], v[216:219], v[74:77]
	v_mfma_f32_16x16x32_bf16 v[66:69], v[184:187], v[216:219], v[66:69]
	s_setprio 0
	s_barrier
; #define PG8_STAGE(bufoff, gbase, voff) do { _Pragma("unroll") for (int _i = 0; _i < 2; ++_i) \
;         __builtin_amdgcn_global_load_lds((const unsigned*)((const char*)(gbase) + (voff)[_i]), (PG8_LAS unsigned*)(lds + (bufoff) + ldsw + _i * 8192), 16, 0, 0); } while (0)
; #define PG8_WAIT_V(n) asm volatile("s_waitcnt vmcnt(" #n ")" ::: "memory")
; #define PG8_WAIT_L(n) asm volatile("s_waitcnt lgkmcnt(" #n ")" ::: "memory")
; #define PG8_BAR __builtin_amdgcn_s_barrier()
; #define PG8_SCHED __builtin_amdgcn_sched_barrier(0)
;     __device__ __forceinline__ int nt(const pg8::Unit& u) const { return u.kind == 0 ? ntiles : q_nt(u.kind - 1); }
; template <class Epi, class Sched, bool ALIGN_EPI = true, bool SP2 = true>
; __device__ __forceinline__ void gemm_phase(PG8_LAS unsigned char* lds, const int K  , const Sched& S, const Epi& E) {
;     ...
;         for (int t = 0; t < nt; t += 2) {
;     ...
;             PG8_LDA(At, 1, 1); PG8_STAGE(PG8_SB(1, 0), b3, voffB); PG8_STAGE(PG8_SB(1, 1), b3 + hstep, voffB); PG8_STAGE(PG8_SA(1, 0), a3, voffA);
;             PG8_WAIT_V(8); PG8_WAIT_L(0); PG8_BAR; PG8_MMA(1, 0, At, B0); PG8_MMA(1, 1, At, B1); PG8_BAR; PG8_SCHED;
	s_add_i32 s24, s49, s29
	v_lshl_add_u64 v[220:221], v[220:221], 0, s[6:7]
	s_mov_b32 m0, s24
	ds_read_b128 v[188:191], v156 offset:49152
	ds_read_b128 v[192:195], v156 offset:50176
	ds_read_b128 v[196:199], v156 offset:51200
	ds_read_b128 v[200:203], v156 offset:52224
	ds_read_b128 v[204:207], v156 offset:53248
	ds_read_b128 v[208:211], v156 offset:54272
	ds_read_b128 v[212:215], v156 offset:55296
	ds_read_b128 v[216:219], v156 offset:56320
	global_load_lds_dwordx4 v[220:221], off
	s_add_i32 m0, s24, 0x2000
	s_add_u32 s22, s22, 0x80080
	v_lshl_add_u64 v[220:221], v[222:223], 0, s[6:7]
	s_addc_u32 s23, s23, 0
	s_add_i32 s24, s50, s29
	global_load_lds_dwordx4 v[220:221], off
	v_lshl_add_u64 v[220:221], s[22:23], 0, v[136:137]
	s_mov_b32 m0, s24
	s_nop 0
	global_load_lds_dwordx4 v[220:221], off
	v_lshl_add_u64 v[220:221], s[22:23], 0, v[132:133]
	s_add_i32 m0, s24, 0x2000
	s_nop 0
	global_load_lds_dwordx4 v[220:221], off
	v_lshl_add_u64 v[220:221], v[224:225], 0, s[6:7]
	s_mov_b32 m0, s36
	s_nop 0
	global_load_lds_dwordx4 v[220:221], off
	v_lshl_add_u64 v[220:221], v[226:227], 0, s[6:7]
	s_mov_b32 m0, s37
	s_nop 0
	global_load_lds_dwordx4 v[220:221], off
	s_waitcnt vmcnt(8)
	s_waitcnt lgkmcnt(0)
	s_barrier
	s_setprio 1
	s_waitcnt lgkmcnt(0)
	v_mfma_f32_16x16x32_bf16 v[62:65], v[148:151], v[188:191], v[62:65]
	v_mfma_f32_16x16x32_bf16 v[54:57], v[164:167], v[188:191], v[54:57]
	v_mfma_f32_16x16x32_bf16 v[46:49], v[148:151], v[196:199], v[46:49]
	v_mfma_f32_16x16x32_bf16 v[38:41], v[164:167], v[196:199], v[38:41]
	v_mfma_f32_16x16x32_bf16 v[30:33], v[148:151], v[204:207], v[30:33]
	v_mfma_f32_16x16x32_bf16 v[22:25], v[164:167], v[204:207], v[22:25]
	v_mfma_f32_16x16x32_bf16 v[14:17], v[148:151], v[212:215], v[14:17]
	v_mfma_f32_16x16x32_bf16 v[6:9], v[164:167], v[212:215], v[6:9]
	v_mfma_f32_16x16x32_bf16 v[62:65], v[160:163], v[192:195], v[62:65]
	v_mfma_f32_16x16x32_bf16 v[54:57], v[168:171], v[192:195], v[54:57]
	v_mfma_f32_16x16x32_bf16 v[46:49], v[160:163], v[200:203], v[46:49]
	v_mfma_f32_16x16x32_bf16 v[38:41], v[168:171], v[200:203], v[38:41]
	v_mfma_f32_16x16x32_bf16 v[30:33], v[160:163], v[208:211], v[30:33]
	v_mfma_f32_16x16x32_bf16 v[22:25], v[168:171], v[208:211], v[22:25]
	v_mfma_f32_16x16x32_bf16 v[14:17], v[160:163], v[216:219], v[14:17]
	v_mfma_f32_16x16x32_bf16 v[6:9], v[168:171], v[216:219], v[6:9]
	s_setprio 0
	s_setprio 1
	v_mfma_f32_16x16x32_bf16 v[58:61], v[172:175], v[188:191], v[58:61]
	v_mfma_f32_16x16x32_bf16 v[50:53], v[180:183], v[188:191], v[50:53]
	v_mfma_f32_16x16x32_bf16 v[42:45], v[172:175], v[196:199], v[42:45]
	v_mfma_f32_16x16x32_bf16 v[34:37], v[180:183], v[196:199], v[34:37]
	v_mfma_f32_16x16x32_bf16 v[26:29], v[172:175], v[204:207], v[26:29]
	v_mfma_f32_16x16x32_bf16 v[18:21], v[180:183], v[204:207], v[18:21]
	v_mfma_f32_16x16x32_bf16 v[10:13], v[172:175], v[212:215], v[10:13]
	v_mfma_f32_16x16x32_bf16 v[2:5], v[180:183], v[212:215], v[2:5]
	v_mfma_f32_16x16x32_bf16 v[58:61], v[176:179], v[192:195], v[58:61]
	v_mfma_f32_16x16x32_bf16 v[50:53], v[184:187], v[192:195], v[50:53]
	v_mfma_f32_16x16x32_bf16 v[42:45], v[176:179], v[200:203], v[42:45]
	v_mfma_f32_16x16x32_bf16 v[34:37], v[184:187], v[200:203], v[34:37]
	v_mfma_f32_16x16x32_bf16 v[26:29], v[176:179], v[208:211], v[26:29]
	v_mfma_f32_16x16x32_bf16 v[18:21], v[184:187], v[208:211], v[18:21]
	v_mfma_f32_16x16x32_bf16 v[10:13], v[176:179], v[216:219], v[10:13]
	v_mfma_f32_16x16x32_bf16 v[2:5], v[184:187], v[216:219], v[2:5]
	s_setprio 0
	s_barrier
	s_add_i32 s48, s48, 2
	s_add_u32 s20, s20, 0x100
	s_addc_u32 s21, s21, 0
	s_add_u32 s46, s46, 0x100
	s_addc_u32 s47, s47, 0
	s_cmp_gt_u32 s48, 29
	s_cbranch_scc0 .LBB0_219
	s_nop 0
	s_and_b64 vcc, exec, s[8:9]
	s_cbranch_vccz .LBB0_222
	s_barrier

; #define PG8_STAGE(bufoff, gbase, voff) do { _Pragma("unroll") for (int _i = 0; _i < 2; ++_i) \
;         __builtin_amdgcn_global_load_lds((const unsigned*)((const char*)(gbase) + (voff)[_i]), (PG8_LAS unsigned*)(lds + (bufoff) + ldsw + _i * 8192), 16, 0, 0); } while (0)
; #define PG8_SCHED __builtin_amdgcn_sched_barrier(0)
;     __device__ __forceinline__ int nt(const pg8::Unit& u) const { return u.kind == 0 ? ntiles : q_nt(u.kind - 1); }
;     __device__ __forceinline__ const char* a_base(const pg8::Unit& u) const { return A + (size_t)u.pm * tstep + (u.kind > 1 ? (size_t)q_off(u.kind - 1) * 128 : 0); }
;     __device__ __forceinline__ const char* b_base(const pg8::Unit& u) const { return Bt + (size_t)u.pn * tstep + (u.kind > 1 ? (size_t)q_off(u.kind - 1) * 128 : 0); }
; template <class Epi, class Sched, bool ALIGN_EPI = true, bool SP2 = true>
; __device__ __forceinline__ void gemm_phase(PG8_LAS unsigned char* lds, const int K  , const Sched& S, const Epi& E) {
;     ...
;         const int nt = S.nt(cur);
;         const char* nA = has_next ? S.a_base(nxt) : cA; const char* nB = has_next ? S.b_base(nxt) : cB;
;         for (int t = 0; t < nt; t += 2) {
;             const bool last = (t == nt - 2);
;             const char* a1 = cA + (size_t)(t + 1) * kstep;
;             const char* a2 = last ? nA : cA + (size_t)(t + 2) * kstep; const char* b2 = last ? nB : cB + (size_t)(t + 2) * kstep;
;             const char* a3 = a2 + kstep; const char* b3 = b2 + kstep;
;             if constexpr (SP2) {
;             PG8_LDB(B0, 0, 0); PG8_LDB(B1, 0, 1); PG8_SCHED; PG8_LDA(At, 0, 0); PG8_STAGE(PG8_SA(1, 1), a1 + hstep, voffA);
;     ...
; #pragma unroll
;         for (int a = 0; a < 2; ++a)
; #pragma unroll
;             for (int b = 0; b < 2; ++b)
; #pragma unroll
;                 for (int m = 0; m < 4; ++m)
; #pragma unroll
;                     for (int n = 0; n < 2; ++n) acc[a][b][m][n] = (f32x4){0.f, 0.f, 0.f, 0.f};
.LBB0_954:
	s_cmp_eq_u32 s71, 0
	s_cselect_b32 s4, 32, 8
	s_add_i32 s13, s4, -2
	s_add_u32 s24, s24, 0x80080
	s_addc_u32 s25, s25, 0
	s_add_u32 s15, s26, 0x100
	v_mov_b32_e32 v2, 0
	s_mov_b32 s28, 0
	s_addc_u32 s21, s27, 0
	v_mov_b32_e32 v3, v2
	v_mov_b32_e32 v4, v2
	v_mov_b32_e32 v5, v2
	v_mov_b32_e32 v6, v2
	v_mov_b32_e32 v7, v2
	v_mov_b32_e32 v8, v2
	v_mov_b32_e32 v9, v2
	v_mov_b32_e32 v10, v2
	v_mov_b32_e32 v11, v2
	v_mov_b32_e32 v12, v2
	v_mov_b32_e32 v13, v2
	v_mov_b32_e32 v18, v2
	v_mov_b32_e32 v19, v2
	v_mov_b32_e32 v20, v2
	v_mov_b32_e32 v21, v2
	v_mov_b32_e32 v26, v2
	v_mov_b32_e32 v27, v2
	v_mov_b32_e32 v28, v2
	v_mov_b32_e32 v29, v2
	v_mov_b32_e32 v34, v2
	v_mov_b32_e32 v35, v2
	v_mov_b32_e32 v36, v2
	v_mov_b32_e32 v37, v2
	v_mov_b32_e32 v42, v2
	v_mov_b32_e32 v43, v2
	v_mov_b32_e32 v44, v2
	v_mov_b32_e32 v45, v2
	v_mov_b32_e32 v50, v2
	v_mov_b32_e32 v51, v2
	v_mov_b32_e32 v52, v2
	v_mov_b32_e32 v53, v2
	v_mov_b32_e32 v14, v2
	v_mov_b32_e32 v15, v2
	v_mov_b32_e32 v16, v2
	v_mov_b32_e32 v17, v2
	v_mov_b32_e32 v22, v2
	v_mov_b32_e32 v23, v2
	v_mov_b32_e32 v24, v2
	v_mov_b32_e32 v25, v2
	v_mov_b32_e32 v30, v2
	v_mov_b32_e32 v31, v2
	v_mov_b32_e32 v32, v2
	v_mov_b32_e32 v33, v2
	v_mov_b32_e32 v38, v2
	v_mov_b32_e32 v39, v2
	v_mov_b32_e32 v40, v2
	v_mov_b32_e32 v41, v2
	v_mov_b32_e32 v46, v2
	v_mov_b32_e32 v47, v2
	v_mov_b32_e32 v48, v2
	v_mov_b32_e32 v49, v2
	v_mov_b32_e32 v54, v2
	v_mov_b32_e32 v55, v2
	v_mov_b32_e32 v56, v2
	v_mov_b32_e32 v57, v2
	v_mov_b32_e32 v58, v2
	v_mov_b32_e32 v59, v2
	v_mov_b32_e32 v60, v2
	v_mov_b32_e32 v61, v2
	v_mov_b32_e32 v62, v2
	v_mov_b32_e32 v63, v2
	v_mov_b32_e32 v64, v2
	v_mov_b32_e32 v65, v2
	v_mov_b32_e32 v66, v2
	v_mov_b32_e32 v67, v2
	v_mov_b32_e32 v68, v2
	v_mov_b32_e32 v69, v2
	v_mov_b32_e32 v70, v2
	v_mov_b32_e32 v71, v2
	v_mov_b32_e32 v72, v2
	v_mov_b32_e32 v73, v2
	v_mov_b32_e32 v74, v2
	v_mov_b32_e32 v75, v2
	v_mov_b32_e32 v76, v2
	v_mov_b32_e32 v77, v2
	v_mov_b32_e32 v82, v2
	v_mov_b32_e32 v83, v2
	v_mov_b32_e32 v84, v2
	v_mov_b32_e32 v85, v2
	v_mov_b32_e32 v90, v2
	v_mov_b32_e32 v91, v2
	v_mov_b32_e32 v92, v2
	v_mov_b32_e32 v93, v2
	v_mov_b32_e32 v98, v2
	v_mov_b32_e32 v99, v2
	v_mov_b32_e32 v100, v2
	v_mov_b32_e32 v101, v2
	v_mov_b32_e32 v106, v2
	v_mov_b32_e32 v107, v2
	v_mov_b32_e32 v108, v2
	v_mov_b32_e32 v109, v2
	v_mov_b32_e32 v114, v2
	v_mov_b32_e32 v115, v2
	v_mov_b32_e32 v116, v2
	v_mov_b32_e32 v117, v2
	v_mov_b32_e32 v78, v2
	v_mov_b32_e32 v79, v2
	v_mov_b32_e32 v80, v2
	v_mov_b32_e32 v81, v2
	v_mov_b32_e32 v86, v2
	v_mov_b32_e32 v87, v2
	v_mov_b32_e32 v88, v2
	v_mov_b32_e32 v89, v2
	v_mov_b32_e32 v94, v2
	v_mov_b32_e32 v95, v2
	v_mov_b32_e32 v96, v2
	v_mov_b32_e32 v97, v2
	v_mov_b32_e32 v102, v2
	v_mov_b32_e32 v103, v2
	v_mov_b32_e32 v104, v2
	v_mov_b32_e32 v105, v2
	v_mov_b32_e32 v110, v2
	v_mov_b32_e32 v111, v2
	v_mov_b32_e32 v112, v2
	v_mov_b32_e32 v113, v2
	v_mov_b32_e32 v118, v2
	v_mov_b32_e32 v119, v2
	v_mov_b32_e32 v120, v2
	v_mov_b32_e32 v121, v2
	v_mov_b32_e32 v122, v2
	v_mov_b32_e32 v123, v2
	v_mov_b32_e32 v124, v2
	v_mov_b32_e32 v125, v2
	v_mov_b32_e32 v126, v2
	v_mov_b32_e32 v127, v2
	v_mov_b32_e32 v128, v2
	v_mov_b32_e32 v129, v2
	s_nop 0
.LBB0_955:
	s_waitcnt vmcnt(0)
	ds_read_b128 v[130:133], v232
	ds_read_b128 v[134:137], v232 offset:1024
	ds_read_b128 v[138:141], v232 offset:2048
	ds_read_b128 v[142:145], v232 offset:3072
	ds_read_b128 v[146:149], v233
	ds_read_b128 v[150:153], v233 offset:1024
	ds_read_b128 v[154:157], v233 offset:2048
	ds_read_b128 v[158:161], v233 offset:3072
	s_add_i32 s73, s28, 2
	s_add_u32 s26, s24, 0xfff80080
	s_addc_u32 s27, s25, -1
	s_cmp_eq_u32 s13, s28
	s_cselect_b32 s28, s16, s26
	s_cselect_b32 s29, s17, s27
	s_cselect_b32 s27, s19, s21
	s_cselect_b32 s26, s18, s15
	v_lshl_add_u64 v[194:195], s[24:25], 0, v[214:215]
	s_add_i32 m0, s23, 0xc000
	ds_read_b128 v[162:165], v234
	ds_read_b128 v[166:169], v234 offset:1024
	ds_read_b128 v[170:173], v234 offset:2048
	ds_read_b128 v[174:177], v234 offset:3072
	ds_read_b128 v[178:181], v234 offset:4096
	ds_read_b128 v[182:185], v234 offset:5120
	ds_read_b128 v[186:189], v234 offset:6144
	ds_read_b128 v[190:193], v234 offset:7168
	global_load_lds_dwordx4 v[194:195], off
	v_lshl_add_u64 v[194:195], s[24:25], 0, v[216:217]
	s_add_i32 m0, s23, 0xe000
	s_nop 0
	global_load_lds_dwordx4 v[194:195], off
	s_waitcnt vmcnt(8)
	s_waitcnt lgkmcnt(0)
	s_barrier
	s_setprio 1
	s_waitcnt lgkmcnt(0)
	v_mfma_f32_16x16x32_bf16 v[126:129], v[130:133], v[162:165], v[126:129]
	v_mfma_f32_16x16x32_bf16 v[122:125], v[138:141], v[162:165], v[122:125]
	v_mfma_f32_16x16x32_bf16 v[118:121], v[130:133], v[170:173], v[118:121]
	v_mfma_f32_16x16x32_bf16 v[110:113], v[138:141], v[170:173], v[110:113]
	v_mfma_f32_16x16x32_bf16 v[102:105], v[130:133], v[178:181], v[102:105]
	v_mfma_f32_16x16x32_bf16 v[94:97], v[138:141], v[178:181], v[94:97]
	v_mfma_f32_16x16x32_bf16 v[86:89], v[130:133], v[186:189], v[86:89]
	v_mfma_f32_16x16x32_bf16 v[78:81], v[138:141], v[186:189], v[78:81]
	v_mfma_f32_16x16x32_bf16 v[126:129], v[134:137], v[166:169], v[126:129]
	v_mfma_f32_16x16x32_bf16 v[122:125], v[142:145], v[166:169], v[122:125]
	v_mfma_f32_16x16x32_bf16 v[118:121], v[134:137], v[174:177], v[118:121]
	v_mfma_f32_16x16x32_bf16 v[110:113], v[142:145], v[174:177], v[110:113]
	v_mfma_f32_16x16x32_bf16 v[102:105], v[134:137], v[182:185], v[102:105]
	v_mfma_f32_16x16x32_bf16 v[94:97], v[142:145], v[182:185], v[94:97]
	v_mfma_f32_16x16x32_bf16 v[86:89], v[134:137], v[190:193], v[86:89]
	v_mfma_f32_16x16x32_bf16 v[78:81], v[142:145], v[190:193], v[78:81]
	s_setprio 0
	s_setprio 1
	v_mfma_f32_16x16x32_bf16 v[114:117], v[146:149], v[162:165], v[114:117]
	v_mfma_f32_16x16x32_bf16 v[106:109], v[154:157], v[162:165], v[106:109]
	v_mfma_f32_16x16x32_bf16 v[98:101], v[146:149], v[170:173], v[98:101]
	v_mfma_f32_16x16x32_bf16 v[90:93], v[154:157], v[170:173], v[90:93]
	v_mfma_f32_16x16x32_bf16 v[82:85], v[146:149], v[178:181], v[82:85]
	v_mfma_f32_16x16x32_bf16 v[74:77], v[154:157], v[178:181], v[74:77]
	v_mfma_f32_16x16x32_bf16 v[70:73], v[146:149], v[186:189], v[70:73]
	v_mfma_f32_16x16x32_bf16 v[66:69], v[154:157], v[186:189], v[66:69]
	v_mfma_f32_16x16x32_bf16 v[114:117], v[150:153], v[166:169], v[114:117]
	v_mfma_f32_16x16x32_bf16 v[106:109], v[158:161], v[166:169], v[106:109]
	v_mfma_f32_16x16x32_bf16 v[98:101], v[150:153], v[174:177], v[98:101]
	v_mfma_f32_16x16x32_bf16 v[90:93], v[158:161], v[174:177], v[90:93]
	v_mfma_f32_16x16x32_bf16 v[82:85], v[150:153], v[182:185], v[82:85]
	v_mfma_f32_16x16x32_bf16 v[74:77], v[158:161], v[182:185], v[74:77]
	v_mfma_f32_16x16x32_bf16 v[70:73], v[150:153], v[190:193], v[70:73]
	v_mfma_f32_16x16x32_bf16 v[66:69], v[158:161], v[190:193], v[66:69]
	s_setprio 0
	s_barrier
; #define PG8_STAGE(bufoff, gbase, voff) do { _Pragma("unroll") for (int _i = 0; _i < 2; ++_i) \
;         __builtin_amdgcn_global_load_lds((const unsigned*)((const char*)(gbase) + (voff)[_i]), (PG8_LAS unsigned*)(lds + (bufoff) + ldsw + _i * 8192), 16, 0, 0); } while (0)
; #define PG8_WAIT_V(n) asm volatile("s_waitcnt vmcnt(" #n ")" ::: "memory")
; #define PG8_WAIT_L(n) asm volatile("s_waitcnt lgkmcnt(" #n ")" ::: "memory")
; #define PG8_BAR __builtin_amdgcn_s_barrier()
; #define PG8_SCHED __builtin_amdgcn_sched_barrier(0)
; template <class Epi, class Sched, bool ALIGN_EPI = true, bool SP2 = true>
; __device__ __forceinline__ void gemm_phase(PG8_LAS unsigned char* lds, const int K  , const Sched& S, const Epi& E) {
;     ...
;             PG8_LDA(At, 0, 1); PG8_STAGE(PG8_SB(0, 0), b2, voffB); PG8_STAGE(PG8_SB(0, 1), b2 + hstep, voffB); PG8_STAGE(PG8_SA(0, 0), a2, voffA);
;             PG8_WAIT_V(8); PG8_WAIT_L(0); PG8_BAR; PG8_MMA(1, 0, At, B0); PG8_MMA(1, 1, At, B1); PG8_BAR; PG8_SCHED;
;             PG8_LDB(B0, 1, 0); PG8_LDB(B1, 1, 1); PG8_SCHED; PG8_LDA(At, 1, 0); PG8_STAGE(PG8_SA(0, 1), a2 + hstep, voffA);
	s_add_i32 s74, s47, s33
	v_lshl_add_u64 v[194:195], s[26:27], 0, v[208:209]
	s_mov_b32 m0, s74
	ds_read_b128 v[162:165], v234 offset:16384
	ds_read_b128 v[166:169], v234 offset:17408
	ds_read_b128 v[170:173], v234 offset:18432
	ds_read_b128 v[174:177], v234 offset:19456
	ds_read_b128 v[178:181], v234 offset:20480
	ds_read_b128 v[182:185], v234 offset:21504
	ds_read_b128 v[186:189], v234 offset:22528
	ds_read_b128 v[190:193], v234 offset:23552
	global_load_lds_dwordx4 v[194:195], off
	s_add_i32 m0, s74, 0x2000
	s_add_u32 s74, s26, 0x80000
	v_lshl_add_u64 v[196:197], s[26:27], 0, v[212:213]
	s_addc_u32 s75, s27, 0
	s_add_i32 s76, s48, s33
	global_load_lds_dwordx4 v[196:197], off
	v_lshl_add_u64 v[198:199], s[74:75], 0, v[208:209]
	s_mov_b32 m0, s76
	v_lshl_add_u64 v[200:201], s[28:29], 0, v[210:211]
	global_load_lds_dwordx4 v[198:199], off
	v_lshl_add_u64 v[198:199], s[74:75], 0, v[212:213]
	s_add_i32 m0, s76, 0x2000
	s_nop 0
	global_load_lds_dwordx4 v[198:199], off
	v_lshl_add_u64 v[198:199], s[28:29], 0, v[206:207]
	s_mov_b32 m0, s23
	s_nop 0
	global_load_lds_dwordx4 v[198:199], off
	s_mov_b32 m0, s34
	s_nop 0
	global_load_lds_dwordx4 v[200:201], off
	s_waitcnt vmcnt(8)
	s_waitcnt lgkmcnt(0)
	s_barrier
	s_setprio 1
	s_waitcnt lgkmcnt(0)
	v_mfma_f32_16x16x32_bf16 v[62:65], v[130:133], v[162:165], v[62:65]
	v_mfma_f32_16x16x32_bf16 v[58:61], v[138:141], v[162:165], v[58:61]
	v_mfma_f32_16x16x32_bf16 v[54:57], v[130:133], v[170:173], v[54:57]
	v_mfma_f32_16x16x32_bf16 v[46:49], v[138:141], v[170:173], v[46:49]
	v_mfma_f32_16x16x32_bf16 v[38:41], v[130:133], v[178:181], v[38:41]
	v_mfma_f32_16x16x32_bf16 v[30:33], v[138:141], v[178:181], v[30:33]
	v_mfma_f32_16x16x32_bf16 v[22:25], v[130:133], v[186:189], v[22:25]
	v_mfma_f32_16x16x32_bf16 v[14:17], v[138:141], v[186:189], v[14:17]
	v_mfma_f32_16x16x32_bf16 v[62:65], v[134:137], v[166:169], v[62:65]
	v_mfma_f32_16x16x32_bf16 v[58:61], v[142:145], v[166:169], v[58:61]
	v_mfma_f32_16x16x32_bf16 v[54:57], v[134:137], v[174:177], v[54:57]
	v_mfma_f32_16x16x32_bf16 v[46:49], v[142:145], v[174:177], v[46:49]
	v_mfma_f32_16x16x32_bf16 v[38:41], v[134:137], v[182:185], v[38:41]
	v_mfma_f32_16x16x32_bf16 v[30:33], v[142:145], v[182:185], v[30:33]
	v_mfma_f32_16x16x32_bf16 v[22:25], v[134:137], v[190:193], v[22:25]
	v_mfma_f32_16x16x32_bf16 v[14:17], v[142:145], v[190:193], v[14:17]
	s_setprio 0
	s_setprio 1
	v_mfma_f32_16x16x32_bf16 v[50:53], v[146:149], v[162:165], v[50:53]
	v_mfma_f32_16x16x32_bf16 v[42:45], v[154:157], v[162:165], v[42:45]
	v_mfma_f32_16x16x32_bf16 v[34:37], v[146:149], v[170:173], v[34:37]
	v_mfma_f32_16x16x32_bf16 v[26:29], v[154:157], v[170:173], v[26:29]
	v_mfma_f32_16x16x32_bf16 v[18:21], v[146:149], v[178:181], v[18:21]
	v_mfma_f32_16x16x32_bf16 v[10:13], v[154:157], v[178:181], v[10:13]
	v_mfma_f32_16x16x32_bf16 v[6:9], v[146:149], v[186:189], v[6:9]
	v_mfma_f32_16x16x32_bf16 v[2:5], v[154:157], v[186:189], v[2:5]
	v_mfma_f32_16x16x32_bf16 v[50:53], v[150:153], v[166:169], v[50:53]
	v_mfma_f32_16x16x32_bf16 v[42:45], v[158:161], v[166:169], v[42:45]
	v_mfma_f32_16x16x32_bf16 v[34:37], v[150:153], v[174:177], v[34:37]
	v_mfma_f32_16x16x32_bf16 v[26:29], v[158:161], v[174:177], v[26:29]
	v_mfma_f32_16x16x32_bf16 v[18:21], v[150:153], v[182:185], v[18:21]
	v_mfma_f32_16x16x32_bf16 v[10:13], v[158:161], v[182:185], v[10:13]
	v_mfma_f32_16x16x32_bf16 v[6:9], v[150:153], v[190:193], v[6:9]
	v_mfma_f32_16x16x32_bf16 v[2:5], v[158:161], v[190:193], v[2:5]
	s_setprio 0
	s_barrier
	s_add_i32 s74, 0, 0x18000
	s_add_i32 s75, 0, 0x1c000
	v_add_u32_e32 v142, s74, v230
	v_add_u32_e32 v158, s75, v230
	ds_read_b128 v[130:133], v142
	ds_read_b128 v[134:137], v142 offset:1024
	ds_read_b128 v[138:141], v142 offset:2048
	ds_read_b128 v[142:145], v142 offset:3072
	ds_read_b128 v[146:149], v158
	ds_read_b128 v[150:153], v158 offset:1024
	ds_read_b128 v[154:157], v158 offset:2048
	ds_read_b128 v[158:161], v158 offset:3072
	s_add_u32 s28, s28, 0x80000
	s_addc_u32 s29, s29, 0
	s_mov_b32 m0, s35
	v_lshl_add_u64 v[202:203], s[28:29], 0, v[206:207]
	ds_read_b128 v[162:165], v234 offset:32768
	ds_read_b128 v[166:169], v234 offset:33792
	ds_read_b128 v[170:173], v234 offset:34816
	ds_read_b128 v[174:177], v234 offset:35840
	ds_read_b128 v[178:181], v234 offset:36864
	ds_read_b128 v[182:185], v234 offset:37888
	ds_read_b128 v[186:189], v234 offset:38912
	ds_read_b128 v[190:193], v234 offset:39936
	global_load_lds_dwordx4 v[202:203], off
	v_lshl_add_u64 v[202:203], s[28:29], 0, v[210:211]
	s_mov_b32 m0, s36
	s_nop 0
	global_load_lds_dwordx4 v[202:203], off
	s_waitcnt vmcnt(8)
	s_waitcnt lgkmcnt(0)
	s_barrier
; #define PG8_STAGE(bufoff, gbase, voff) do { _Pragma("unroll") for (int _i = 0; _i < 2; ++_i) \
;         __builtin_amdgcn_global_load_lds((const unsigned*)((const char*)(gbase) + (voff)[_i]), (PG8_LAS unsigned*)(lds + (bufoff) + ldsw + _i * 8192), 16, 0, 0); } while (0)
; #define PG8_WAIT_V(n) asm volatile("s_waitcnt vmcnt(" #n ")" ::: "memory")
; #define PG8_WAIT_L(n) asm volatile("s_waitcnt lgkmcnt(" #n ")" ::: "memory")
; #define PG8_BAR __builtin_amdgcn_s_barrier()
; #define PG8_SCHED __builtin_amdgcn_sched_barrier(0)
; template <class Epi, class Sched, bool ALIGN_EPI = true, bool SP2 = true>
; __device__ __forceinline__ void gemm_phase(PG8_LAS unsigned char* lds, const int K  , const Sched& S, const Epi& E) {
;     ...
;             PG8_WAIT_V(8); PG8_WAIT_L(0); PG8_BAR; PG8_MMA(0, 0, At, B0); PG8_MMA(0, 1, At, B1); PG8_BAR; PG8_SCHED;
;             PG8_LDA(At, 1, 1); PG8_STAGE(PG8_SB(1, 0), b3, voffB); PG8_STAGE(PG8_SB(1, 1), b3 + hstep, voffB); PG8_STAGE(PG8_SA(1, 0), a3, voffA);
;             PG8_WAIT_V(8); PG8_WAIT_L(0); PG8_BAR; PG8_MMA(1, 0, At, B0); PG8_MMA(1, 1, At, B1); PG8_BAR; PG8_SCHED;
	s_setprio 1
	s_waitcnt lgkmcnt(0)
	v_mfma_f32_16x16x32_bf16 v[126:129], v[130:133], v[162:165], v[126:129]
	v_mfma_f32_16x16x32_bf16 v[122:125], v[138:141], v[162:165], v[122:125]
	v_mfma_f32_16x16x32_bf16 v[118:121], v[130:133], v[170:173], v[118:121]
	v_mfma_f32_16x16x32_bf16 v[110:113], v[138:141], v[170:173], v[110:113]
	v_mfma_f32_16x16x32_bf16 v[102:105], v[130:133], v[178:181], v[102:105]
	v_mfma_f32_16x16x32_bf16 v[94:97], v[138:141], v[178:181], v[94:97]
	v_mfma_f32_16x16x32_bf16 v[86:89], v[130:133], v[186:189], v[86:89]
	v_mfma_f32_16x16x32_bf16 v[78:81], v[138:141], v[186:189], v[78:81]
	v_mfma_f32_16x16x32_bf16 v[126:129], v[134:137], v[166:169], v[126:129]
	v_mfma_f32_16x16x32_bf16 v[122:125], v[142:145], v[166:169], v[122:125]
	v_mfma_f32_16x16x32_bf16 v[118:121], v[134:137], v[174:177], v[118:121]
	v_mfma_f32_16x16x32_bf16 v[110:113], v[142:145], v[174:177], v[110:113]
	v_mfma_f32_16x16x32_bf16 v[102:105], v[134:137], v[182:185], v[102:105]
	v_mfma_f32_16x16x32_bf16 v[94:97], v[142:145], v[182:185], v[94:97]
	v_mfma_f32_16x16x32_bf16 v[86:89], v[134:137], v[190:193], v[86:89]
	v_mfma_f32_16x16x32_bf16 v[78:81], v[142:145], v[190:193], v[78:81]
	s_setprio 0
	s_setprio 1
	v_mfma_f32_16x16x32_bf16 v[114:117], v[146:149], v[162:165], v[114:117]
	v_mfma_f32_16x16x32_bf16 v[106:109], v[154:157], v[162:165], v[106:109]
	v_mfma_f32_16x16x32_bf16 v[98:101], v[146:149], v[170:173], v[98:101]
	v_mfma_f32_16x16x32_bf16 v[90:93], v[154:157], v[170:173], v[90:93]
	v_mfma_f32_16x16x32_bf16 v[82:85], v[146:149], v[178:181], v[82:85]
	v_mfma_f32_16x16x32_bf16 v[74:77], v[154:157], v[178:181], v[74:77]
	v_mfma_f32_16x16x32_bf16 v[70:73], v[146:149], v[186:189], v[70:73]
	v_mfma_f32_16x16x32_bf16 v[66:69], v[154:157], v[186:189], v[66:69]
	v_mfma_f32_16x16x32_bf16 v[114:117], v[150:153], v[166:169], v[114:117]
	v_mfma_f32_16x16x32_bf16 v[106:109], v[158:161], v[166:169], v[106:109]
	v_mfma_f32_16x16x32_bf16 v[98:101], v[150:153], v[174:177], v[98:101]
	v_mfma_f32_16x16x32_bf16 v[90:93], v[158:161], v[174:177], v[90:93]
	v_mfma_f32_16x16x32_bf16 v[82:85], v[150:153], v[182:185], v[82:85]
	v_mfma_f32_16x16x32_bf16 v[74:77], v[158:161], v[182:185], v[74:77]
	v_mfma_f32_16x16x32_bf16 v[70:73], v[150:153], v[190:193], v[70:73]
	v_mfma_f32_16x16x32_bf16 v[66:69], v[158:161], v[190:193], v[66:69]
	s_setprio 0
	s_barrier
	s_add_i32 s28, s74, s33
	v_lshl_add_u64 v[194:195], v[194:195], 0, s[8:9]
	s_mov_b32 m0, s28
	ds_read_b128 v[162:165], v234 offset:49152
	ds_read_b128 v[166:169], v234 offset:50176
	ds_read_b128 v[170:173], v234 offset:51200
	ds_read_b128 v[174:177], v234 offset:52224
	ds_read_b128 v[178:181], v234 offset:53248
	ds_read_b128 v[182:185], v234 offset:54272
	ds_read_b128 v[186:189], v234 offset:55296
	ds_read_b128 v[190:193], v234 offset:56320
	global_load_lds_dwordx4 v[194:195], off
	s_add_i32 m0, s28, 0x2000
	s_add_u32 s26, s26, 0x80080
	v_lshl_add_u64 v[194:195], v[196:197], 0, s[8:9]
	s_addc_u32 s27, s27, 0
	s_add_i32 s28, s75, s33
	global_load_lds_dwordx4 v[194:195], off
	v_lshl_add_u64 v[194:195], s[26:27], 0, v[208:209]
	s_mov_b32 m0, s28
	s_nop 0
	global_load_lds_dwordx4 v[194:195], off
	v_lshl_add_u64 v[194:195], s[26:27], 0, v[212:213]
	s_add_i32 m0, s28, 0x2000
	s_nop 0
	global_load_lds_dwordx4 v[194:195], off
	v_lshl_add_u64 v[194:195], v[198:199], 0, s[8:9]
	s_mov_b32 m0, s42
	s_nop 0
	global_load_lds_dwordx4 v[194:195], off
	v_lshl_add_u64 v[194:195], v[200:201], 0, s[8:9]
	s_mov_b32 m0, s43
	s_nop 0
	global_load_lds_dwordx4 v[194:195], off
	s_waitcnt vmcnt(8)
	s_waitcnt lgkmcnt(0)
	s_barrier
	s_setprio 1
	s_waitcnt lgkmcnt(0)
	v_mfma_f32_16x16x32_bf16 v[62:65], v[130:133], v[162:165], v[62:65]
	v_mfma_f32_16x16x32_bf16 v[58:61], v[138:141], v[162:165], v[58:61]
	v_mfma_f32_16x16x32_bf16 v[54:57], v[130:133], v[170:173], v[54:57]
	v_mfma_f32_16x16x32_bf16 v[46:49], v[138:141], v[170:173], v[46:49]
	v_mfma_f32_16x16x32_bf16 v[38:41], v[130:133], v[178:181], v[38:41]
	v_mfma_f32_16x16x32_bf16 v[30:33], v[138:141], v[178:181], v[30:33]
	v_mfma_f32_16x16x32_bf16 v[22:25], v[130:133], v[186:189], v[22:25]
	v_mfma_f32_16x16x32_bf16 v[14:17], v[138:141], v[186:189], v[14:17]
	v_mfma_f32_16x16x32_bf16 v[62:65], v[134:137], v[166:169], v[62:65]
	v_mfma_f32_16x16x32_bf16 v[58:61], v[142:145], v[166:169], v[58:61]
	v_mfma_f32_16x16x32_bf16 v[54:57], v[134:137], v[174:177], v[54:57]
	v_mfma_f32_16x16x32_bf16 v[46:49], v[142:145], v[174:177], v[46:49]
	v_mfma_f32_16x16x32_bf16 v[38:41], v[134:137], v[182:185], v[38:41]
	v_mfma_f32_16x16x32_bf16 v[30:33], v[142:145], v[182:185], v[30:33]
	v_mfma_f32_16x16x32_bf16 v[22:25], v[134:137], v[190:193], v[22:25]
	v_mfma_f32_16x16x32_bf16 v[14:17], v[142:145], v[190:193], v[14:17]
	s_setprio 0
	s_setprio 1
	v_mfma_f32_16x16x32_bf16 v[50:53], v[146:149], v[162:165], v[50:53]
	v_mfma_f32_16x16x32_bf16 v[42:45], v[154:157], v[162:165], v[42:45]
	v_mfma_f32_16x16x32_bf16 v[34:37], v[146:149], v[170:173], v[34:37]
	v_mfma_f32_16x16x32_bf16 v[26:29], v[154:157], v[170:173], v[26:29]
	v_mfma_f32_16x16x32_bf16 v[18:21], v[146:149], v[178:181], v[18:21]
	v_mfma_f32_16x16x32_bf16 v[10:13], v[154:157], v[178:181], v[10:13]
	v_mfma_f32_16x16x32_bf16 v[6:9], v[146:149], v[186:189], v[6:9]
	v_mfma_f32_16x16x32_bf16 v[2:5], v[154:157], v[186:189], v[2:5]
	v_mfma_f32_16x16x32_bf16 v[50:53], v[150:153], v[166:169], v[50:53]
	v_mfma_f32_16x16x32_bf16 v[42:45], v[158:161], v[166:169], v[42:45]
	v_mfma_f32_16x16x32_bf16 v[34:37], v[150:153], v[174:177], v[34:37]
	v_mfma_f32_16x16x32_bf16 v[26:29], v[158:161], v[174:177], v[26:29]
	v_mfma_f32_16x16x32_bf16 v[18:21], v[150:153], v[182:185], v[18:21]
	v_mfma_f32_16x16x32_bf16 v[10:13], v[158:161], v[182:185], v[10:13]
	v_mfma_f32_16x16x32_bf16 v[6:9], v[150:153], v[190:193], v[6:9]
	v_mfma_f32_16x16x32_bf16 v[2:5], v[158:161], v[190:193], v[2:5]
	s_setprio 0
	s_barrier
	s_add_u32 s24, s24, 0x100
	s_addc_u32 s25, s25, 0
	s_add_u32 s15, s15, 0x100
	s_addc_u32 s21, s21, 0
	s_cmp_ge_u32 s73, s4
	s_mov_b32 s28, s73
	s_cbranch_scc0 .LBB0_955
	s_nop 0
	s_and_b64 vcc, exec, s[10:11]
	s_cbranch_vccz .LBB0_958
	s_barrier

; #define PG8_STAGE(bufoff, gbase, voff) do { _Pragma("unroll") for (int _i = 0; _i < 2; ++_i) \
;         __builtin_amdgcn_global_load_lds((const unsigned*)((const char*)(gbase) + (voff)[_i]), (PG8_LAS unsigned*)(lds + (bufoff) + ldsw + _i * 8192), 16, 0, 0); } while (0)
; #define PG8_SCHED __builtin_amdgcn_sched_barrier(0)
;     __device__ __forceinline__ int nt(const pg8::Unit& u) const { return u.kind == 0 ? ntiles : q_nt(u.kind - 1); }
;     __device__ __forceinline__ const char* a_base(const pg8::Unit& u) const { return A + (size_t)u.pm * tstep + (u.kind > 1 ? (size_t)q_off(u.kind - 1) * 128 : 0); }
;     __device__ __forceinline__ const char* b_base(const pg8::Unit& u) const { return Bt + (size_t)u.pn * tstep + (u.kind > 1 ? (size_t)q_off(u.kind - 1) * 128 : 0); }
; template <class Epi, class Sched, bool ALIGN_EPI = true, bool SP2 = true>
; __device__ __forceinline__ void gemm_phase(PG8_LAS unsigned char* lds, const int K  , const Sched& S, const Epi& E) {
;     ...
;         const bool has_next = S.next(ui + 1, nxt);
;         const int nt = S.nt(cur);
;         const char* nA = has_next ? S.a_base(nxt) : cA; const char* nB = has_next ? S.b_base(nxt) : cB;
;         for (int t = 0; t < nt; t += 2) {
;             const bool last = (t == nt - 2);
;             const char* a1 = cA + (size_t)(t + 1) * kstep;
;             const char* a2 = last ? nA : cA + (size_t)(t + 2) * kstep; const char* b2 = last ? nB : cB + (size_t)(t + 2) * kstep;
;             const char* a3 = a2 + kstep; const char* b3 = b2 + kstep;
;             if constexpr (SP2) {
;             PG8_LDB(B0, 0, 0); PG8_LDB(B1, 0, 1); PG8_SCHED; PG8_LDA(At, 0, 0); PG8_STAGE(PG8_SA(1, 1), a1 + hstep, voffA);
;     ...
; #pragma unroll
;         for (int a = 0; a < 2; ++a)
; #pragma unroll
;             for (int b = 0; b < 2; ++b)
; #pragma unroll
;                 for (int m = 0; m < 4; ++m)
; #pragma unroll
;                     for (int n = 0; n < 2; ++n) acc[a][b][m][n] = (f32x4){0.f, 0.f, 0.f, 0.f};
.LBB0_1098:
	s_ashr_i32 s15, s14, 31
	s_lshl_b64 s[16:17], s[14:15], 20
	v_readlane_b32 s6, v253, 48
	s_add_u32 s16, s6, s16
	v_readlane_b32 s6, v253, 49
	s_addc_u32 s17, s6, s17
	s_and_b64 s[18:19], s[0:1], exec
	s_cselect_b32 s15, s17, s23
	s_cselect_b32 s44, s16, s22
	s_ashr_i32 s11, s10, 31
	s_lshl_b64 s[18:19], s[10:11], 20
	s_add_u32 s18, s94, s18
	s_addc_u32 s19, s95, s19
	s_and_b64 s[26:27], s[0:1], exec
	s_cselect_b32 s11, s19, s25
	s_cselect_b32 s45, s18, s24
	s_add_u32 s22, s22, 0x80080
	s_addc_u32 s23, s23, 0
	s_add_u32 s46, s24, 0x100
	v_mov_b32_e32 v2, 0
	s_addc_u32 s47, s25, 0
	s_mov_b32 s48, -2
	v_mov_b32_e32 v3, v2
	v_mov_b32_e32 v4, v2
	v_mov_b32_e32 v5, v2
	v_mov_b32_e32 v10, v2
	v_mov_b32_e32 v11, v2
	v_mov_b32_e32 v12, v2
	v_mov_b32_e32 v13, v2
	v_mov_b32_e32 v18, v2
	v_mov_b32_e32 v19, v2
	v_mov_b32_e32 v20, v2
	v_mov_b32_e32 v21, v2
	v_mov_b32_e32 v26, v2
	v_mov_b32_e32 v27, v2
	v_mov_b32_e32 v28, v2
	v_mov_b32_e32 v29, v2
	v_mov_b32_e32 v34, v2
	v_mov_b32_e32 v35, v2
	v_mov_b32_e32 v36, v2
	v_mov_b32_e32 v37, v2
	v_mov_b32_e32 v42, v2
	v_mov_b32_e32 v43, v2
	v_mov_b32_e32 v44, v2
	v_mov_b32_e32 v45, v2
	v_mov_b32_e32 v50, v2
	v_mov_b32_e32 v51, v2
	v_mov_b32_e32 v52, v2
	v_mov_b32_e32 v53, v2
	v_mov_b32_e32 v58, v2
	v_mov_b32_e32 v59, v2
	v_mov_b32_e32 v60, v2
	v_mov_b32_e32 v61, v2
	v_mov_b32_e32 v6, v2
	v_mov_b32_e32 v7, v2
	v_mov_b32_e32 v8, v2
	v_mov_b32_e32 v9, v2
	v_mov_b32_e32 v14, v2
	v_mov_b32_e32 v15, v2
	v_mov_b32_e32 v16, v2
	v_mov_b32_e32 v17, v2
	v_mov_b32_e32 v22, v2
	v_mov_b32_e32 v23, v2
	v_mov_b32_e32 v24, v2
	v_mov_b32_e32 v25, v2
	v_mov_b32_e32 v30, v2
	v_mov_b32_e32 v31, v2
	v_mov_b32_e32 v32, v2
	v_mov_b32_e32 v33, v2
	v_mov_b32_e32 v38, v2
	v_mov_b32_e32 v39, v2
	v_mov_b32_e32 v40, v2
	v_mov_b32_e32 v41, v2
	v_mov_b32_e32 v46, v2
	v_mov_b32_e32 v47, v2
	v_mov_b32_e32 v48, v2
	v_mov_b32_e32 v49, v2
	v_mov_b32_e32 v54, v2
	v_mov_b32_e32 v55, v2
	v_mov_b32_e32 v56, v2
	v_mov_b32_e32 v57, v2
	v_mov_b32_e32 v62, v2
	v_mov_b32_e32 v63, v2
	v_mov_b32_e32 v64, v2
	v_mov_b32_e32 v65, v2
	v_mov_b32_e32 v66, v2
	v_mov_b32_e32 v67, v2
	v_mov_b32_e32 v68, v2
	v_mov_b32_e32 v69, v2
	v_mov_b32_e32 v74, v2
	v_mov_b32_e32 v75, v2
	v_mov_b32_e32 v76, v2
	v_mov_b32_e32 v77, v2
	v_mov_b32_e32 v82, v2
	v_mov_b32_e32 v83, v2
	v_mov_b32_e32 v84, v2
	v_mov_b32_e32 v85, v2
	v_mov_b32_e32 v90, v2
	v_mov_b32_e32 v91, v2
	v_mov_b32_e32 v92, v2
	v_mov_b32_e32 v93, v2
	v_mov_b32_e32 v98, v2
	v_mov_b32_e32 v99, v2
	v_mov_b32_e32 v100, v2
	v_mov_b32_e32 v101, v2
	v_mov_b32_e32 v106, v2
	v_mov_b32_e32 v107, v2
	v_mov_b32_e32 v108, v2
	v_mov_b32_e32 v109, v2
	v_mov_b32_e32 v114, v2
	v_mov_b32_e32 v115, v2
	v_mov_b32_e32 v116, v2
	v_mov_b32_e32 v117, v2
	v_mov_b32_e32 v122, v2
	v_mov_b32_e32 v123, v2
	v_mov_b32_e32 v124, v2
	v_mov_b32_e32 v125, v2
	v_mov_b32_e32 v70, v2
	v_mov_b32_e32 v71, v2
	v_mov_b32_e32 v72, v2
	v_mov_b32_e32 v73, v2
	v_mov_b32_e32 v78, v2
	v_mov_b32_e32 v79, v2
	v_mov_b32_e32 v80, v2
	v_mov_b32_e32 v81, v2
	v_mov_b32_e32 v86, v2
	v_mov_b32_e32 v87, v2
	v_mov_b32_e32 v88, v2
	v_mov_b32_e32 v89, v2
	v_mov_b32_e32 v94, v2
	v_mov_b32_e32 v95, v2
	v_mov_b32_e32 v96, v2
	v_mov_b32_e32 v97, v2
	v_mov_b32_e32 v102, v2
	v_mov_b32_e32 v103, v2
	v_mov_b32_e32 v104, v2
	v_mov_b32_e32 v105, v2
	v_mov_b32_e32 v110, v2
	v_mov_b32_e32 v111, v2
	v_mov_b32_e32 v112, v2
	v_mov_b32_e32 v113, v2
	v_mov_b32_e32 v118, v2
	v_mov_b32_e32 v119, v2
	v_mov_b32_e32 v120, v2
	v_mov_b32_e32 v121, v2
	v_mov_b32_e32 v126, v2
	v_mov_b32_e32 v127, v2
	v_mov_b32_e32 v128, v2
	v_mov_b32_e32 v129, v2
	s_nop 0
.LBB0_1099:
	ds_read_b128 v[148:151], v154
	ds_read_b128 v[160:163], v154 offset:1024
	ds_read_b128 v[164:167], v154 offset:2048
	ds_read_b128 v[168:171], v154 offset:3072
	ds_read_b128 v[172:175], v155
	ds_read_b128 v[176:179], v155 offset:1024
	ds_read_b128 v[180:183], v155 offset:2048
	ds_read_b128 v[184:187], v155 offset:3072
	s_add_u32 s24, s22, 0xfff80080
	s_addc_u32 s25, s23, -1
	s_cmp_eq_u32 s48, 28
	s_cselect_b32 s27, s15, s25
	s_cselect_b32 s26, s44, s24
	s_cselect_b32 s25, s11, s47
	s_cselect_b32 s24, s45, s46
	v_lshl_add_u64 v[220:221], s[22:23], 0, v[140:141]
	s_add_i32 m0, s21, 0xc000
	ds_read_b128 v[188:191], v156
	ds_read_b128 v[192:195], v156 offset:1024
	ds_read_b128 v[196:199], v156 offset:2048
	ds_read_b128 v[200:203], v156 offset:3072
	ds_read_b128 v[204:207], v156 offset:4096
	ds_read_b128 v[208:211], v156 offset:5120
	ds_read_b128 v[212:215], v156 offset:6144
	ds_read_b128 v[216:219], v156 offset:7168
	global_load_lds_dwordx4 v[220:221], off
	v_lshl_add_u64 v[220:221], s[22:23], 0, v[142:143]
	s_add_i32 m0, s21, 0xe000
	s_nop 0
	global_load_lds_dwordx4 v[220:221], off
	s_waitcnt vmcnt(8)
	s_waitcnt lgkmcnt(0)
	s_barrier
; #define PG8_STAGE(bufoff, gbase, voff) do { _Pragma("unroll") for (int _i = 0; _i < 2; ++_i) \
;         __builtin_amdgcn_global_load_lds((const unsigned*)((const char*)(gbase) + (voff)[_i]), (PG8_LAS unsigned*)(lds + (bufoff) + ldsw + _i * 8192), 16, 0, 0); } while (0)
; #define PG8_WAIT_V(n) asm volatile("s_waitcnt vmcnt(" #n ")" ::: "memory")
; #define PG8_WAIT_L(n) asm volatile("s_waitcnt lgkmcnt(" #n ")" ::: "memory")
; #define PG8_BAR __builtin_amdgcn_s_barrier()
; #define PG8_SCHED __builtin_amdgcn_sched_barrier(0)
; template <class Epi, class Sched, bool ALIGN_EPI = true, bool SP2 = true>
; __device__ __forceinline__ void gemm_phase(PG8_LAS unsigned char* lds, const int K  , const Sched& S, const Epi& E) {
;     ...
;             PG8_WAIT_V(8); PG8_WAIT_L(0); PG8_BAR; PG8_MMA(0, 0, At, B0); PG8_MMA(0, 1, At, B1); PG8_BAR; PG8_SCHED;
;             PG8_LDA(At, 0, 1); PG8_STAGE(PG8_SB(0, 0), b2, voffB); PG8_STAGE(PG8_SB(0, 1), b2 + hstep, voffB); PG8_STAGE(PG8_SA(0, 0), a2, voffA);
;             PG8_WAIT_V(8); PG8_WAIT_L(0); PG8_BAR; PG8_MMA(1, 0, At, B0); PG8_MMA(1, 1, At, B1); PG8_BAR; PG8_SCHED;
	s_setprio 1
	s_waitcnt lgkmcnt(0)
	v_mfma_f32_16x16x32_bf16 v[126:129], v[148:151], v[188:191], v[126:129]
	v_mfma_f32_16x16x32_bf16 v[118:121], v[164:167], v[188:191], v[118:121]
	v_mfma_f32_16x16x32_bf16 v[110:113], v[148:151], v[196:199], v[110:113]
	v_mfma_f32_16x16x32_bf16 v[102:105], v[164:167], v[196:199], v[102:105]
	v_mfma_f32_16x16x32_bf16 v[94:97], v[148:151], v[204:207], v[94:97]
	v_mfma_f32_16x16x32_bf16 v[86:89], v[164:167], v[204:207], v[86:89]
	v_mfma_f32_16x16x32_bf16 v[78:81], v[148:151], v[212:215], v[78:81]
	v_mfma_f32_16x16x32_bf16 v[70:73], v[164:167], v[212:215], v[70:73]
	v_mfma_f32_16x16x32_bf16 v[126:129], v[160:163], v[192:195], v[126:129]
	v_mfma_f32_16x16x32_bf16 v[118:121], v[168:171], v[192:195], v[118:121]
	v_mfma_f32_16x16x32_bf16 v[110:113], v[160:163], v[200:203], v[110:113]
	v_mfma_f32_16x16x32_bf16 v[102:105], v[168:171], v[200:203], v[102:105]
	v_mfma_f32_16x16x32_bf16 v[94:97], v[160:163], v[208:211], v[94:97]
	v_mfma_f32_16x16x32_bf16 v[86:89], v[168:171], v[208:211], v[86:89]
	v_mfma_f32_16x16x32_bf16 v[78:81], v[160:163], v[216:219], v[78:81]
	v_mfma_f32_16x16x32_bf16 v[70:73], v[168:171], v[216:219], v[70:73]
	s_setprio 0
	s_setprio 1
	v_mfma_f32_16x16x32_bf16 v[122:125], v[172:175], v[188:191], v[122:125]
	v_mfma_f32_16x16x32_bf16 v[114:117], v[180:183], v[188:191], v[114:117]
	v_mfma_f32_16x16x32_bf16 v[106:109], v[172:175], v[196:199], v[106:109]
	v_mfma_f32_16x16x32_bf16 v[98:101], v[180:183], v[196:199], v[98:101]
	v_mfma_f32_16x16x32_bf16 v[90:93], v[172:175], v[204:207], v[90:93]
	v_mfma_f32_16x16x32_bf16 v[82:85], v[180:183], v[204:207], v[82:85]
	v_mfma_f32_16x16x32_bf16 v[74:77], v[172:175], v[212:215], v[74:77]
	v_mfma_f32_16x16x32_bf16 v[66:69], v[180:183], v[212:215], v[66:69]
	v_mfma_f32_16x16x32_bf16 v[122:125], v[176:179], v[192:195], v[122:125]
	v_mfma_f32_16x16x32_bf16 v[114:117], v[184:187], v[192:195], v[114:117]
	v_mfma_f32_16x16x32_bf16 v[106:109], v[176:179], v[200:203], v[106:109]
	v_mfma_f32_16x16x32_bf16 v[98:101], v[184:187], v[200:203], v[98:101]
	v_mfma_f32_16x16x32_bf16 v[90:93], v[176:179], v[208:211], v[90:93]
	v_mfma_f32_16x16x32_bf16 v[82:85], v[184:187], v[208:211], v[82:85]
	v_mfma_f32_16x16x32_bf16 v[74:77], v[176:179], v[216:219], v[74:77]
	v_mfma_f32_16x16x32_bf16 v[66:69], v[184:187], v[216:219], v[66:69]
	s_setprio 0
	s_barrier
	s_add_i32 s49, s39, s29
	v_lshl_add_u64 v[220:221], s[24:25], 0, v[136:137]
	s_mov_b32 m0, s49
	ds_read_b128 v[188:191], v156 offset:16384
	ds_read_b128 v[192:195], v156 offset:17408
	ds_read_b128 v[196:199], v156 offset:18432
	ds_read_b128 v[200:203], v156 offset:19456
	ds_read_b128 v[204:207], v156 offset:20480
	ds_read_b128 v[208:211], v156 offset:21504
	ds_read_b128 v[212:215], v156 offset:22528
	ds_read_b128 v[216:219], v156 offset:23552
	global_load_lds_dwordx4 v[220:221], off
	s_add_i32 m0, s49, 0x2000
	s_add_u32 s50, s24, 0x80000
	v_lshl_add_u64 v[222:223], s[24:25], 0, v[132:133]
	s_addc_u32 s51, s25, 0
	s_add_i32 s49, s40, s29
	global_load_lds_dwordx4 v[222:223], off
	v_lshl_add_u64 v[224:225], s[50:51], 0, v[136:137]
	s_mov_b32 m0, s49
	v_lshl_add_u64 v[226:227], s[26:27], 0, v[134:135]
	global_load_lds_dwordx4 v[224:225], off
	v_lshl_add_u64 v[224:225], s[50:51], 0, v[132:133]
	s_add_i32 m0, s49, 0x2000
	s_nop 0
	global_load_lds_dwordx4 v[224:225], off
	v_lshl_add_u64 v[224:225], s[26:27], 0, v[138:139]
	s_mov_b32 m0, s21
	s_nop 0
	global_load_lds_dwordx4 v[224:225], off
	s_mov_b32 m0, s31
	s_nop 0
	global_load_lds_dwordx4 v[226:227], off
	s_waitcnt vmcnt(8)
	s_waitcnt lgkmcnt(0)
	s_barrier
	s_setprio 1
	s_waitcnt lgkmcnt(0)
	v_mfma_f32_16x16x32_bf16 v[62:65], v[148:151], v[188:191], v[62:65]
	v_mfma_f32_16x16x32_bf16 v[54:57], v[164:167], v[188:191], v[54:57]
	v_mfma_f32_16x16x32_bf16 v[46:49], v[148:151], v[196:199], v[46:49]
	v_mfma_f32_16x16x32_bf16 v[38:41], v[164:167], v[196:199], v[38:41]
	v_mfma_f32_16x16x32_bf16 v[30:33], v[148:151], v[204:207], v[30:33]
	v_mfma_f32_16x16x32_bf16 v[22:25], v[164:167], v[204:207], v[22:25]
	v_mfma_f32_16x16x32_bf16 v[14:17], v[148:151], v[212:215], v[14:17]
	v_mfma_f32_16x16x32_bf16 v[6:9], v[164:167], v[212:215], v[6:9]
	v_mfma_f32_16x16x32_bf16 v[62:65], v[160:163], v[192:195], v[62:65]
	v_mfma_f32_16x16x32_bf16 v[54:57], v[168:171], v[192:195], v[54:57]
	v_mfma_f32_16x16x32_bf16 v[46:49], v[160:163], v[200:203], v[46:49]
	v_mfma_f32_16x16x32_bf16 v[38:41], v[168:171], v[200:203], v[38:41]
	v_mfma_f32_16x16x32_bf16 v[30:33], v[160:163], v[208:211], v[30:33]
	v_mfma_f32_16x16x32_bf16 v[22:25], v[168:171], v[208:211], v[22:25]
	v_mfma_f32_16x16x32_bf16 v[14:17], v[160:163], v[216:219], v[14:17]
	v_mfma_f32_16x16x32_bf16 v[6:9], v[168:171], v[216:219], v[6:9]
	s_setprio 0
	s_setprio 1
	v_mfma_f32_16x16x32_bf16 v[58:61], v[172:175], v[188:191], v[58:61]
	v_mfma_f32_16x16x32_bf16 v[50:53], v[180:183], v[188:191], v[50:53]
	v_mfma_f32_16x16x32_bf16 v[42:45], v[172:175], v[196:199], v[42:45]
	v_mfma_f32_16x16x32_bf16 v[34:37], v[180:183], v[196:199], v[34:37]
	v_mfma_f32_16x16x32_bf16 v[26:29], v[172:175], v[204:207], v[26:29]
	v_mfma_f32_16x16x32_bf16 v[18:21], v[180:183], v[204:207], v[18:21]
	v_mfma_f32_16x16x32_bf16 v[10:13], v[172:175], v[212:215], v[10:13]
	v_mfma_f32_16x16x32_bf16 v[2:5], v[180:183], v[212:215], v[2:5]
	v_mfma_f32_16x16x32_bf16 v[58:61], v[176:179], v[192:195], v[58:61]
	v_mfma_f32_16x16x32_bf16 v[50:53], v[184:187], v[192:195], v[50:53]
	v_mfma_f32_16x16x32_bf16 v[42:45], v[176:179], v[200:203], v[42:45]
	v_mfma_f32_16x16x32_bf16 v[34:37], v[184:187], v[200:203], v[34:37]
	v_mfma_f32_16x16x32_bf16 v[26:29], v[176:179], v[208:211], v[26:29]
	v_mfma_f32_16x16x32_bf16 v[18:21], v[184:187], v[208:211], v[18:21]
	v_mfma_f32_16x16x32_bf16 v[10:13], v[176:179], v[216:219], v[10:13]
	v_mfma_f32_16x16x32_bf16 v[2:5], v[184:187], v[216:219], v[2:5]
	s_setprio 0
	s_barrier
; #define PG8_STAGE(bufoff, gbase, voff) do { _Pragma("unroll") for (int _i = 0; _i < 2; ++_i) \
;         __builtin_amdgcn_global_load_lds((const unsigned*)((const char*)(gbase) + (voff)[_i]), (PG8_LAS unsigned*)(lds + (bufoff) + ldsw + _i * 8192), 16, 0, 0); } while (0)
; #define PG8_WAIT_V(n) asm volatile("s_waitcnt vmcnt(" #n ")" ::: "memory")
; #define PG8_WAIT_L(n) asm volatile("s_waitcnt lgkmcnt(" #n ")" ::: "memory")
; #define PG8_BAR __builtin_amdgcn_s_barrier()
; #define PG8_SCHED __builtin_amdgcn_sched_barrier(0)
; template <class Epi, class Sched, bool ALIGN_EPI = true, bool SP2 = true>
; __device__ __forceinline__ void gemm_phase(PG8_LAS unsigned char* lds, const int K  , const Sched& S, const Epi& E) {
;     ...
;             PG8_LDB(B0, 1, 0); PG8_LDB(B1, 1, 1); PG8_SCHED; PG8_LDA(At, 1, 0); PG8_STAGE(PG8_SA(0, 1), a2 + hstep, voffA);
;             PG8_WAIT_V(8); PG8_WAIT_L(0); PG8_BAR; PG8_MMA(0, 0, At, B0); PG8_MMA(0, 1, At, B1); PG8_BAR; PG8_SCHED;
	s_add_i32 s49, 0, 0x18000
	v_add_u32_e32 v159, s49, v152
	s_add_i32 s50, 0, 0x1c000
	ds_read_b128 v[148:151], v159
	ds_read_b128 v[160:163], v159 offset:1024
	ds_read_b128 v[164:167], v159 offset:2048
	ds_read_b128 v[168:171], v159 offset:3072
	v_add_u32_e32 v159, s50, v152
	ds_read_b128 v[172:175], v159
	ds_read_b128 v[176:179], v159 offset:1024
	ds_read_b128 v[180:183], v159 offset:2048
	ds_read_b128 v[184:187], v159 offset:3072
	s_add_u32 s26, s26, 0x80000
	s_addc_u32 s27, s27, 0
	s_mov_b32 m0, s33
	v_lshl_add_u64 v[230:231], s[26:27], 0, v[138:139]
	ds_read_b128 v[188:191], v156 offset:32768
	ds_read_b128 v[192:195], v156 offset:33792
	ds_read_b128 v[196:199], v156 offset:34816
	ds_read_b128 v[200:203], v156 offset:35840
	ds_read_b128 v[204:207], v156 offset:36864
	ds_read_b128 v[208:211], v156 offset:37888
	ds_read_b128 v[212:215], v156 offset:38912
	ds_read_b128 v[216:219], v156 offset:39936
	global_load_lds_dwordx4 v[230:231], off
	v_lshl_add_u64 v[230:231], s[26:27], 0, v[134:135]
	s_mov_b32 m0, s34
	s_nop 0
	global_load_lds_dwordx4 v[230:231], off
	s_waitcnt vmcnt(8)
	s_waitcnt lgkmcnt(0)
	s_barrier
	s_setprio 1
	s_waitcnt lgkmcnt(0)
	v_mfma_f32_16x16x32_bf16 v[126:129], v[148:151], v[188:191], v[126:129]
	v_mfma_f32_16x16x32_bf16 v[118:121], v[164:167], v[188:191], v[118:121]
	v_mfma_f32_16x16x32_bf16 v[110:113], v[148:151], v[196:199], v[110:113]
	v_mfma_f32_16x16x32_bf16 v[102:105], v[164:167], v[196:199], v[102:105]
	v_mfma_f32_16x16x32_bf16 v[94:97], v[148:151], v[204:207], v[94:97]
	v_mfma_f32_16x16x32_bf16 v[86:89], v[164:167], v[204:207], v[86:89]
	v_mfma_f32_16x16x32_bf16 v[78:81], v[148:151], v[212:215], v[78:81]
	v_mfma_f32_16x16x32_bf16 v[70:73], v[164:167], v[212:215], v[70:73]
	v_mfma_f32_16x16x32_bf16 v[126:129], v[160:163], v[192:195], v[126:129]
	v_mfma_f32_16x16x32_bf16 v[118:121], v[168:171], v[192:195], v[118:121]
	v_mfma_f32_16x16x32_bf16 v[110:113], v[160:163], v[200:203], v[110:113]
	v_mfma_f32_16x16x32_bf16 v[102:105], v[168:171], v[200:203], v[102:105]
	v_mfma_f32_16x16x32_bf16 v[94:97], v[160:163], v[208:211], v[94:97]
	v_mfma_f32_16x16x32_bf16 v[86:89], v[168:171], v[208:211], v[86:89]
	v_mfma_f32_16x16x32_bf16 v[78:81], v[160:163], v[216:219], v[78:81]
	v_mfma_f32_16x16x32_bf16 v[70:73], v[168:171], v[216:219], v[70:73]
	s_setprio 0
	s_setprio 1
	v_mfma_f32_16x16x32_bf16 v[122:125], v[172:175], v[188:191], v[122:125]
	v_mfma_f32_16x16x32_bf16 v[114:117], v[180:183], v[188:191], v[114:117]
	v_mfma_f32_16x16x32_bf16 v[106:109], v[172:175], v[196:199], v[106:109]
	v_mfma_f32_16x16x32_bf16 v[98:101], v[180:183], v[196:199], v[98:101]
	v_mfma_f32_16x16x32_bf16 v[90:93], v[172:175], v[204:207], v[90:93]
	v_mfma_f32_16x16x32_bf16 v[82:85], v[180:183], v[204:207], v[82:85]
	v_mfma_f32_16x16x32_bf16 v[74:77], v[172:175], v[212:215], v[74:77]
	v_mfma_f32_16x16x32_bf16 v[66:69], v[180:183], v[212:215], v[66:69]
	v_mfma_f32_16x16x32_bf16 v[122:125], v[176:179], v[192:195], v[122:125]
	v_mfma_f32_16x16x32_bf16 v[114:117], v[184:187], v[192:195], v[114:117]
	v_mfma_f32_16x16x32_bf16 v[106:109], v[176:179], v[200:203], v[106:109]
	v_mfma_f32_16x16x32_bf16 v[98:101], v[184:187], v[200:203], v[98:101]
	v_mfma_f32_16x16x32_bf16 v[90:93], v[176:179], v[208:211], v[90:93]
	v_mfma_f32_16x16x32_bf16 v[82:85], v[184:187], v[208:211], v[82:85]
	v_mfma_f32_16x16x32_bf16 v[74:77], v[176:179], v[216:219], v[74:77]
	v_mfma_f32_16x16x32_bf16 v[66:69], v[184:187], v[216:219], v[66:69]
	s_setprio 0
	s_barrier
; #define PG8_STAGE(bufoff, gbase, voff) do { _Pragma("unroll") for (int _i = 0; _i < 2; ++_i) \
;         __builtin_amdgcn_global_load_lds((const unsigned*)((const char*)(gbase) + (voff)[_i]), (PG8_LAS unsigned*)(lds + (bufoff) + ldsw + _i * 8192), 16, 0, 0); } while (0)
; #define PG8_WAIT_V(n) asm volatile("s_waitcnt vmcnt(" #n ")" ::: "memory")
; #define PG8_WAIT_L(n) asm volatile("s_waitcnt lgkmcnt(" #n ")" ::: "memory")
; #define PG8_BAR __builtin_amdgcn_s_barrier()
; #define PG8_SCHED __builtin_amdgcn_sched_barrier(0)
;     __device__ __forceinline__ int nt(const pg8::Unit& u) const { return u.kind == 0 ? ntiles : q_nt(u.kind - 1); }
; template <class Epi, class Sched, bool ALIGN_EPI = true, bool SP2 = true>
; __device__ __forceinline__ void gemm_phase(PG8_LAS unsigned char* lds, const int K  , const Sched& S, const Epi& E) {
;     ...
;         for (int t = 0; t < nt; t += 2) {
;     ...
;             PG8_LDA(At, 1, 1); PG8_STAGE(PG8_SB(1, 0), b3, voffB); PG8_STAGE(PG8_SB(1, 1), b3 + hstep, voffB); PG8_STAGE(PG8_SA(1, 0), a3, voffA);
;             PG8_WAIT_V(8); PG8_WAIT_L(0); PG8_BAR; PG8_MMA(1, 0, At, B0); PG8_MMA(1, 1, At, B1); PG8_BAR; PG8_SCHED;
	s_add_i32 s26, s49, s29
	v_lshl_add_u64 v[220:221], v[220:221], 0, s[4:5]
	s_mov_b32 m0, s26
	ds_read_b128 v[188:191], v156 offset:49152
	ds_read_b128 v[192:195], v156 offset:50176
	ds_read_b128 v[196:199], v156 offset:51200
	ds_read_b128 v[200:203], v156 offset:52224
	ds_read_b128 v[204:207], v156 offset:53248
	ds_read_b128 v[208:211], v156 offset:54272
	ds_read_b128 v[212:215], v156 offset:55296
	ds_read_b128 v[216:219], v156 offset:56320
	global_load_lds_dwordx4 v[220:221], off
	s_add_i32 m0, s26, 0x2000
	s_add_u32 s24, s24, 0x80080
	v_lshl_add_u64 v[220:221], v[222:223], 0, s[4:5]
	s_addc_u32 s25, s25, 0
	s_add_i32 s26, s50, s29
	global_load_lds_dwordx4 v[220:221], off
	v_lshl_add_u64 v[220:221], s[24:25], 0, v[136:137]
	s_mov_b32 m0, s26
	s_nop 0
	global_load_lds_dwordx4 v[220:221], off
	v_lshl_add_u64 v[220:221], s[24:25], 0, v[132:133]
	s_add_i32 m0, s26, 0x2000
	s_nop 0
	global_load_lds_dwordx4 v[220:221], off
	v_lshl_add_u64 v[220:221], v[224:225], 0, s[4:5]
	s_mov_b32 m0, s36
	s_nop 0
	global_load_lds_dwordx4 v[220:221], off
	v_lshl_add_u64 v[220:221], v[226:227], 0, s[4:5]
	s_mov_b32 m0, s37
	s_nop 0
	global_load_lds_dwordx4 v[220:221], off
	s_waitcnt vmcnt(8)
	s_waitcnt lgkmcnt(0)
	s_barrier
	s_setprio 1
	s_waitcnt lgkmcnt(0)
	v_mfma_f32_16x16x32_bf16 v[62:65], v[148:151], v[188:191], v[62:65]
	v_mfma_f32_16x16x32_bf16 v[54:57], v[164:167], v[188:191], v[54:57]
	v_mfma_f32_16x16x32_bf16 v[46:49], v[148:151], v[196:199], v[46:49]
	v_mfma_f32_16x16x32_bf16 v[38:41], v[164:167], v[196:199], v[38:41]
	v_mfma_f32_16x16x32_bf16 v[30:33], v[148:151], v[204:207], v[30:33]
	v_mfma_f32_16x16x32_bf16 v[22:25], v[164:167], v[204:207], v[22:25]
	v_mfma_f32_16x16x32_bf16 v[14:17], v[148:151], v[212:215], v[14:17]
	v_mfma_f32_16x16x32_bf16 v[6:9], v[164:167], v[212:215], v[6:9]
	v_mfma_f32_16x16x32_bf16 v[62:65], v[160:163], v[192:195], v[62:65]
	v_mfma_f32_16x16x32_bf16 v[54:57], v[168:171], v[192:195], v[54:57]
	v_mfma_f32_16x16x32_bf16 v[46:49], v[160:163], v[200:203], v[46:49]
	v_mfma_f32_16x16x32_bf16 v[38:41], v[168:171], v[200:203], v[38:41]
	v_mfma_f32_16x16x32_bf16 v[30:33], v[160:163], v[208:211], v[30:33]
	v_mfma_f32_16x16x32_bf16 v[22:25], v[168:171], v[208:211], v[22:25]
	v_mfma_f32_16x16x32_bf16 v[14:17], v[160:163], v[216:219], v[14:17]
	v_mfma_f32_16x16x32_bf16 v[6:9], v[168:171], v[216:219], v[6:9]
	s_setprio 0
	s_setprio 1
	v_mfma_f32_16x16x32_bf16 v[58:61], v[172:175], v[188:191], v[58:61]
	v_mfma_f32_16x16x32_bf16 v[50:53], v[180:183], v[188:191], v[50:53]
	v_mfma_f32_16x16x32_bf16 v[42:45], v[172:175], v[196:199], v[42:45]
	v_mfma_f32_16x16x32_bf16 v[34:37], v[180:183], v[196:199], v[34:37]
	v_mfma_f32_16x16x32_bf16 v[26:29], v[172:175], v[204:207], v[26:29]
	v_mfma_f32_16x16x32_bf16 v[18:21], v[180:183], v[204:207], v[18:21]
	v_mfma_f32_16x16x32_bf16 v[10:13], v[172:175], v[212:215], v[10:13]
	v_mfma_f32_16x16x32_bf16 v[2:5], v[180:183], v[212:215], v[2:5]
	v_mfma_f32_16x16x32_bf16 v[58:61], v[176:179], v[192:195], v[58:61]
	v_mfma_f32_16x16x32_bf16 v[50:53], v[184:187], v[192:195], v[50:53]
	v_mfma_f32_16x16x32_bf16 v[42:45], v[176:179], v[200:203], v[42:45]
	v_mfma_f32_16x16x32_bf16 v[34:37], v[184:187], v[200:203], v[34:37]
	v_mfma_f32_16x16x32_bf16 v[26:29], v[176:179], v[208:211], v[26:29]
	v_mfma_f32_16x16x32_bf16 v[18:21], v[184:187], v[208:211], v[18:21]
	v_mfma_f32_16x16x32_bf16 v[10:13], v[176:179], v[216:219], v[10:13]
	v_mfma_f32_16x16x32_bf16 v[2:5], v[184:187], v[216:219], v[2:5]
	s_setprio 0
	s_barrier
	s_add_i32 s48, s48, 2
	s_add_u32 s22, s22, 0x100
	s_addc_u32 s23, s23, 0
	s_add_u32 s46, s46, 0x100
	s_addc_u32 s47, s47, 0
	s_cmp_gt_u32 s48, 29
	s_cbranch_scc0 .LBB0_1099
	s_nop 0
	s_and_b64 vcc, exec, s[8:9]
	s_cbranch_vccz .LBB0_1102
	s_barrier
